# diff-attention loops: exps of the previous tile moved from the QK section into the PV section of the previous step (both layers)
# speedup vs baseline: 1.0120x; 1.0104x over previous
.LBB0_904:
	v_add_f32_e32 v1, v1, v116
	s_add_u32 s0, s18, 0x240000
	v_add_f32_e32 v1, 0, v1
	v_add_f32_e32 v66, v66, v67
	s_addc_u32 s1, s19, 0
	v_add_f32_e32 v1, v1, v66
	v_lshl_add_u64 v[66:67], v[72:73], 1, s[0:1]
	s_mov_b32 m0, s35
	v_exp_f32_e32 v175, v106
	global_load_lds_dwordx4 v[66:67], off
	v_lshl_add_u64 v[66:67], v[70:71], 1, s[0:1]
	s_mov_b32 m0, s86
	v_exp_f32_e32 v176, v107
	global_load_lds_dwordx4 v[66:67], off
	v_exp_f32_e32 v177, v108
	v_exp_f32_e32 v178, v109
	v_exp_f32_e32 v179, v110
	v_exp_f32_e32 v180, v111
	v_exp_f32_e32 v181, v112
	v_exp_f32_e32 v192, v113
	ds_read_b128 v[66:69], v188 offset:40960
	ds_read_b128 v[70:73], v188 offset:45056
	ds_read_b128 v[106:109], v189 offset:40960
	ds_read_b128 v[110:113], v189 offset:45056
	ds_read_b128 v[116:119], v190 offset:40960
	ds_read_b128 v[120:123], v190 offset:45056
	ds_read_b128 v[124:127], v191 offset:40960
	ds_read_b128 v[170:173], v191 offset:45056
	v_exp_f32_e32 v151, v98
	v_exp_f32_e32 v153, v99
	v_exp_f32_e32 v155, v100
	v_exp_f32_e32 v157, v101
	v_exp_f32_e32 v159, v102
	v_exp_f32_e32 v161, v103
	v_exp_f32_e32 v163, v104
	v_exp_f32_e32 v174, v105
	s_waitcnt lgkmcnt(0)
	v_mfma_f32_32x32x16_bf16 v[90:105], v[66:69], v[128:131], 0
	v_exp_f32_e32 v193, v74
	v_exp_f32_e32 v194, v75
	v_exp_f32_e32 v195, v76
	v_exp_f32_e32 v196, v77
	v_exp_f32_e32 v197, v78
	v_exp_f32_e32 v198, v79
	v_exp_f32_e32 v199, v80
	v_exp_f32_e32 v200, v81
	v_mfma_f32_32x32x16_bf16 v[66:81], v[70:73], v[128:131], 0
	v_mfma_f32_32x32x16_bf16 v[90:105], v[106:109], v[132:135], v[90:105]
	v_exp_f32_e32 v82, v82
	v_exp_f32_e32 v83, v83
	v_exp_f32_e32 v84, v84
	v_exp_f32_e32 v85, v85
	v_exp_f32_e32 v86, v86
	v_exp_f32_e32 v87, v87
	v_exp_f32_e32 v88, v88
	v_mfma_f32_32x32x16_bf16 v[66:81], v[110:113], v[132:135], v[66:81]
	v_exp_f32_e32 v89, v89
	v_add_f32_e32 v106, v151, v153
	v_add_f32_e32 v107, v193, v194
	v_mfma_f32_32x32x16_bf16 v[90:105], v[116:119], v[136:139], v[90:105]
	v_add_f32_e32 v106, v106, v155
	v_add_f32_e32 v107, v107, v195
	v_cvt_pk_bf16_f32 v108, v159, v161
	v_add_f32_e32 v106, v106, v157
	v_add_f32_e32 v107, v107, v196
	v_cvt_pk_bf16_f32 v109, v163, v174
	v_add_f32_e32 v106, v106, v159
	v_add_f32_e32 v107, v107, v197
	v_mfma_f32_32x32x16_bf16 v[66:81], v[120:123], v[136:139], v[66:81]
	v_add_f32_e32 v106, v106, v161
	v_add_f32_e32 v107, v107, v198
	s_nop 0
	v_add_f32_e32 v106, v106, v163
	v_add_f32_e32 v107, v107, v199
	s_nop 0
	v_add_f32_e32 v106, v106, v174
	v_add_f32_e32 v107, v107, v200
	s_nop 0
	v_add_f32_e32 v106, v106, v175
	v_add_f32_e32 v107, v107, v82
	s_nop 0
	v_add_f32_e32 v106, v106, v176
	v_add_f32_e32 v107, v107, v83
	s_nop 0
	v_add_f32_e32 v106, v106, v177
	v_add_f32_e32 v107, v107, v84
	s_nop 0
	v_add_f32_e32 v106, v106, v178
	v_add_f32_e32 v107, v107, v85
	s_nop 0
	v_add_f32_e32 v106, v106, v179
	v_add_f32_e32 v107, v107, v86
	s_nop 0
	v_add_f32_e32 v106, v106, v180
	v_add_f32_e32 v107, v107, v87
	s_nop 0
	v_add_f32_e32 v106, v106, v181
	v_add_f32_e32 v107, v107, v88
	s_nop 0
	v_add_f32_e32 v106, v106, v192
	v_add_f32_e32 v107, v107, v89
	s_nop 0
	v_add_f32_e32 v106, v106, v107
	v_mov_b32_e32 v107, v106
	s_nop 1
	v_permlane32_swap_b32_e32 v106, v107
	v_add_f32_e32 v106, v106, v107
	v_add_f32_e32 v149, v1, v106
	v_cvt_pk_bf16_f32 v106, v151, v153
	v_cvt_pk_bf16_f32 v107, v155, v157
	s_nop 0
	v_permlane32_swap_b32_e32 v106, v108
	v_permlane32_swap_b32_e32 v107, v109
	v_mfma_f32_32x32x16_bf16 v[90:105], v[124:127], v[140:143], v[90:105]
	v_cvt_pk_bf16_f32 v110, v175, v176
	v_cvt_pk_bf16_f32 v111, v177, v178
	v_cvt_pk_bf16_f32 v112, v179, v180
	v_cvt_pk_bf16_f32 v113, v181, v192
	v_cvt_pk_bf16_f32 v116, v193, v194
	v_cvt_pk_bf16_f32 v117, v195, v196
	v_cvt_pk_bf16_f32 v118, v197, v198
	v_mfma_f32_32x32x16_bf16 v[66:81], v[170:173], v[140:143], v[66:81]
	v_cvt_pk_bf16_f32 v119, v199, v200
	v_cvt_pk_bf16_f32 v120, v82, v83
	v_cvt_pk_bf16_f32 v121, v84, v85
	v_cvt_pk_bf16_f32 v122, v86, v87
	v_cvt_pk_bf16_f32 v123, v88, v89
	v_permlane32_swap_b32_e32 v110, v112
	v_permlane32_swap_b32_e32 v111, v113
	v_permlane32_swap_b32_e32 v116, v118
	v_permlane32_swap_b32_e32 v117, v119
	v_permlane32_swap_b32_e32 v120, v122
	v_permlane32_swap_b32_e32 v121, v123
	ds_read_b64_tr_b16 v[82:83], v184 offset:0
	ds_read_b64_tr_b16 v[84:85], v184 offset:0x800
	ds_read_b64_tr_b16 v[86:87], v184 offset:0x1000
	ds_read_b64_tr_b16 v[88:89], v184 offset:0x1800
	ds_read_b64_tr_b16 v[124:125], v184 offset:0x2000
	ds_read_b64_tr_b16 v[126:127], v184 offset:0x2800
	ds_read_b64_tr_b16 v[170:171], v184 offset:0x3000
	ds_read_b64_tr_b16 v[172:173], v184 offset:0x3800
	ds_read_b64_tr_b16 v[174:175], v184 offset:0x200
	ds_read_b64_tr_b16 v[176:177], v184 offset:0xa00
	ds_read_b64_tr_b16 v[178:179], v184 offset:0x1200
	ds_read_b64_tr_b16 v[180:181], v184 offset:0x1a00
	ds_read_b64_tr_b16 v[192:193], v184 offset:0x2200
	ds_read_b64_tr_b16 v[194:195], v184 offset:0x2a00
	ds_read_b64_tr_b16 v[196:197], v184 offset:0x3200
	ds_read_b64_tr_b16 v[198:199], v184 offset:0x3a00
	s_waitcnt lgkmcnt(8)
	s_nop 0
	v_mfma_f32_32x32x16_bf16 v[2:17], v[106:109], v[82:85], v[2:17]
	v_exp_f32_e32 v1, v91
	v_exp_f32_e32 v82, v92
	v_exp_f32_e32 v83, v93
	v_mfma_f32_32x32x16_bf16 v[2:17], v[110:113], v[86:89], v[2:17]
	v_exp_f32_e32 v88, v90
	v_mfma_f32_32x32x16_bf16 v[2:17], v[116:119], v[124:127], v[2:17]
	v_mfma_f32_32x32x16_bf16 v[2:17], v[120:123], v[170:173], v[2:17]
	ds_read_b64_tr_b16 v[90:91], v184 offset:0x400
	ds_read_b64_tr_b16 v[92:93], v184 offset:0xc00
	ds_read_b64_tr_b16 v[124:125], v184 offset:0x1400
	ds_read_b64_tr_b16 v[126:127], v184 offset:0x1c00
	ds_read_b64_tr_b16 v[170:171], v184 offset:0x2400
	ds_read_b64_tr_b16 v[172:173], v184 offset:0x2c00
	ds_read_b64_tr_b16 v[200:201], v184 offset:0x3400
	ds_read_b64_tr_b16 v[202:203], v184 offset:0x3c00
	s_waitcnt lgkmcnt(8)
	v_mfma_f32_32x32x16_bf16 v[18:33], v[106:109], v[174:177], v[18:33]
	v_exp_f32_e32 v84, v94
	v_exp_f32_e32 v85, v95
	v_exp_f32_e32 v86, v96
	v_exp_f32_e32 v87, v97
	v_mfma_f32_32x32x16_bf16 v[18:33], v[110:113], v[178:181], v[18:33]
	v_mfma_f32_32x32x16_bf16 v[18:33], v[116:119], v[192:195], v[18:33]
	v_mfma_f32_32x32x16_bf16 v[18:33], v[120:123], v[196:199], v[18:33]
	ds_read_b64_tr_b16 v[94:95], v184 offset:0x600
	ds_read_b64_tr_b16 v[96:97], v184 offset:0xe00
	ds_read_b64_tr_b16 v[174:175], v184 offset:0x1600
	ds_read_b64_tr_b16 v[176:177], v184 offset:0x1e00
	ds_read_b64_tr_b16 v[178:179], v184 offset:0x2600
	ds_read_b64_tr_b16 v[180:181], v184 offset:0x2e00
	ds_read_b64_tr_b16 v[192:193], v184 offset:0x3600
	ds_read_b64_tr_b16 v[194:195], v184 offset:0x3e00
	s_waitcnt lgkmcnt(8)
	v_mfma_f32_32x32x16_bf16 v[34:49], v[106:109], v[90:93], v[34:49]
	v_exp_f32_e32 v90, v98
	v_exp_f32_e32 v89, v99
	v_exp_f32_e32 v92, v100
	v_exp_f32_e32 v91, v101
	v_mfma_f32_32x32x16_bf16 v[34:49], v[110:113], v[124:127], v[34:49]
	v_mfma_f32_32x32x16_bf16 v[34:49], v[116:119], v[170:173], v[34:49]
	v_mfma_f32_32x32x16_bf16 v[34:49], v[120:123], v[200:203], v[34:49]
	s_waitcnt lgkmcnt(0)
	v_mfma_f32_32x32x16_bf16 v[50:65], v[106:109], v[94:97], v[50:65]
	v_exp_f32_e32 v94, v102
	v_exp_f32_e32 v93, v103
	v_exp_f32_e32 v95, v104
	v_exp_f32_e32 v151, v105
	v_mfma_f32_32x32x16_bf16 v[50:65], v[110:113], v[174:177], v[50:65]
	v_mfma_f32_32x32x16_bf16 v[50:65], v[116:119], v[178:181], v[50:65]
	v_mfma_f32_32x32x16_bf16 v[50:65], v[120:123], v[192:195], v[50:65]
	s_waitcnt vmcnt(0)
	s_and_b64 vcc, exec, s[4:5]
	s_waitcnt vmcnt(0)
	s_barrier
	s_cbranch_vccnz .LBB0_911
	v_readlane_b32 s36, v243, 63
	v_readlane_b32 s50, v242, 13
	v_readlane_b32 s51, v242, 14
	s_add_u32 s4, s50, s88
	v_mov_b32_e32 v96, s25
	v_mov_b32_e32 v97, v145
	s_addc_u32 s5, s51, s87
	s_add_i32 s92, s92, s91
	v_lshl_add_u64 v[170:171], v[114:115], 1, v[96:97]
	v_add_u32_e32 v96, s92, v182
	v_add_u32_e32 v97, s10, v166
	v_mul_lo_u32 v96, v96, s22
	v_and_b32_e32 v98, 0x60, v97
	v_or3_b32 v96, v169, v96, v98
	v_ashrrev_i32_e32 v97, 31, v96
	s_add_i32 s90, s90, s89
	v_lshlrev_b64 v[172:173], 1, v[96:97]
	v_add_u32_e32 v96, s90, v182
	v_mul_lo_u32 v96, v96, s22
	v_or3_b32 v96, v169, v96, v98
	v_ashrrev_i32_e32 v97, 31, v96
	v_lshlrev_b64 v[174:175], 1, v[96:97]
	v_or_b32_e32 v172, s24, v172
	v_or_b32_e32 v174, s24, v174
	s_mov_b32 s16, 6
	v_readlane_b32 s37, v242, 0
	v_readlane_b32 s38, v242, 1
	v_readlane_b32 s39, v242, 2
	v_readlane_b32 s40, v242, 3
	v_readlane_b32 s41, v242, 4
	v_readlane_b32 s42, v242, 5
	v_readlane_b32 s43, v242, 6
	v_readlane_b32 s44, v242, 7
	v_readlane_b32 s45, v242, 8
	v_readlane_b32 s46, v242, 9
	v_readlane_b32 s47, v242, 10
	v_readlane_b32 s48, v242, 11
	v_readlane_b32 s49, v242, 12
	v_exp_f32_e32 v222, v66
	v_exp_f32_e32 v223, v67
	v_exp_f32_e32 v224, v68
	v_exp_f32_e32 v225, v69
	v_exp_f32_e32 v226, v70
	v_exp_f32_e32 v227, v71
	v_exp_f32_e32 v228, v72
	v_exp_f32_e32 v229, v73
	v_exp_f32_e32 v230, v74
	v_exp_f32_e32 v231, v75
	v_exp_f32_e32 v232, v76
	v_exp_f32_e32 v233, v77
	v_exp_f32_e32 v234, v78
	v_exp_f32_e32 v235, v79
	v_exp_f32_e32 v236, v80
	v_exp_f32_e32 v237, v81
	s_branch .LBB0_907
.LBB0_906:
	v_lshl_add_u64 v[66:67], v[178:179], 0, s[12:13]
	s_mov_b32 m0, s35
	v_add_f32_e32 v1, v1, v70
	global_load_lds_dwordx4 v[66:67], off
	v_lshl_add_u64 v[66:67], v[176:177], 0, s[12:13]
	s_mov_b32 m0, s86
	global_load_lds_dwordx4 v[66:67], off
	ds_read_b128 v[66:69], v188 offset:40960
	ds_read_b128 v[70:73], v188 offset:45056
	ds_read_b128 v[82:85], v189 offset:40960
	ds_read_b128 v[86:89], v189 offset:45056
	ds_read_b128 v[90:93], v190 offset:40960
	ds_read_b128 v[176:179], v190 offset:45056
	ds_read_b128 v[192:195], v191 offset:40960
	ds_read_b128 v[196:199], v191 offset:45056
	v_add_f32_e32 v1, v149, v1
	s_waitcnt lgkmcnt(0)
	v_mfma_f32_32x32x16_bf16 v[112:127], v[66:69], v[128:131], 0
	v_mfma_f32_32x32x16_bf16 v[66:81], v[70:73], v[128:131], 0
	v_mfma_f32_32x32x16_bf16 v[66:81], v[86:89], v[132:135], v[66:81]
	v_mfma_f32_32x32x16_bf16 v[112:127], v[82:85], v[132:135], v[112:127]
	v_add_f32_e32 v86, v238, v239
	v_add_f32_e32 v87, v222, v223
	v_mfma_f32_32x32x16_bf16 v[66:81], v[176:179], v[136:139], v[66:81]
	v_add_f32_e32 v86, v86, v240
	v_add_f32_e32 v87, v87, v224
	v_cvt_pk_bf16_f32 v94, v238, v239
	v_add_f32_e32 v86, v86, v241
	v_add_f32_e32 v87, v87, v225
	v_cvt_pk_bf16_f32 v95, v240, v241
	v_add_f32_e32 v86, v86, v244
	v_add_f32_e32 v87, v87, v226
	v_cvt_pk_bf16_f32 v96, v244, v245
	v_add_f32_e32 v86, v86, v245
	v_add_f32_e32 v87, v87, v227
	v_cvt_pk_bf16_f32 v97, v246, v247
	v_add_f32_e32 v86, v86, v246
	v_add_f32_e32 v87, v87, v228
	s_nop 0
	v_permlane32_swap_b32_e32 v94, v96
	v_add_f32_e32 v86, v86, v247
	v_add_f32_e32 v87, v87, v229
	v_permlane32_swap_b32_e32 v95, v97
	v_add_f32_e32 v86, v86, v248
	v_add_f32_e32 v87, v87, v230
	v_mfma_f32_32x32x16_bf16 v[112:127], v[90:93], v[136:139], v[112:127]
	v_add_f32_e32 v86, v86, v249
	v_add_f32_e32 v87, v87, v231
	v_add_f32_e32 v86, v86, v250
	v_add_f32_e32 v87, v87, v232
	v_add_f32_e32 v86, v86, v251
	v_add_f32_e32 v87, v87, v233
	v_add_f32_e32 v86, v86, v252
	v_add_f32_e32 v87, v87, v234
	v_add_f32_e32 v86, v86, v253
	v_add_f32_e32 v87, v87, v235
	v_add_f32_e32 v86, v86, v254
	v_add_f32_e32 v87, v87, v236
	v_add_f32_e32 v86, v86, v255
	v_add_f32_e32 v87, v87, v237
	v_add_f32_e32 v86, v86, v87
	v_mov_b32_e32 v87, v86
	s_nop 1
	v_permlane32_swap_b32_e32 v86, v87
	v_add_f32_e32 v86, v86, v87
	v_add_f32_e32 v149, v1, v86
	v_mfma_f32_32x32x16_bf16 v[66:81], v[196:199], v[140:143], v[66:81]
	v_cvt_pk_bf16_f32 v98, v248, v249
	v_cvt_pk_bf16_f32 v99, v250, v251
	v_cvt_pk_bf16_f32 v100, v252, v253
	v_cvt_pk_bf16_f32 v101, v254, v255
	v_cvt_pk_bf16_f32 v102, v222, v223
	v_cvt_pk_bf16_f32 v103, v224, v225
	v_cvt_pk_bf16_f32 v104, v226, v227
	v_cvt_pk_bf16_f32 v105, v228, v229
	v_cvt_pk_bf16_f32 v106, v230, v231
	v_cvt_pk_bf16_f32 v107, v232, v233
	v_cvt_pk_bf16_f32 v108, v234, v235
	v_cvt_pk_bf16_f32 v109, v236, v237
	v_mfma_f32_32x32x16_bf16 v[112:127], v[192:195], v[140:143], v[112:127]
	v_permlane32_swap_b32_e32 v98, v100
	v_permlane32_swap_b32_e32 v99, v101
	v_permlane32_swap_b32_e32 v102, v104
	v_permlane32_swap_b32_e32 v103, v105
	v_permlane32_swap_b32_e32 v106, v108
	v_permlane32_swap_b32_e32 v107, v109
	ds_read_b64_tr_b16 v[82:83], v184 offset:0
	ds_read_b64_tr_b16 v[84:85], v184 offset:0x800
	ds_read_b64_tr_b16 v[86:87], v184 offset:0x1000
	ds_read_b64_tr_b16 v[88:89], v184 offset:0x1800
	ds_read_b64_tr_b16 v[90:91], v184 offset:0x2000
	ds_read_b64_tr_b16 v[92:93], v184 offset:0x2800
	ds_read_b64_tr_b16 v[176:177], v184 offset:0x3000
	ds_read_b64_tr_b16 v[178:179], v184 offset:0x3800
	ds_read_b64_tr_b16 v[192:193], v184 offset:0x200
	ds_read_b64_tr_b16 v[194:195], v184 offset:0xa00
	ds_read_b64_tr_b16 v[196:197], v184 offset:0x1200
	ds_read_b64_tr_b16 v[198:199], v184 offset:0x1a00
	ds_read_b64_tr_b16 v[200:201], v184 offset:0x2200
	ds_read_b64_tr_b16 v[202:203], v184 offset:0x2a00
	ds_read_b64_tr_b16 v[204:205], v184 offset:0x3200
	ds_read_b64_tr_b16 v[206:207], v184 offset:0x3a00
	s_waitcnt lgkmcnt(8)
	s_nop 0
	v_mfma_f32_32x32x16_bf16 v[2:17], v[94:97], v[82:85], v[2:17]
	v_exp_f32_e32 v222, v66
	s_nop 3
	v_exp_f32_e32 v1, v113
	v_exp_f32_e32 v82, v114
	v_exp_f32_e32 v83, v115
	v_mfma_f32_32x32x16_bf16 v[2:17], v[98:101], v[86:89], v[2:17]
	v_exp_f32_e32 v223, v67
	v_exp_f32_e32 v88, v112
	v_mfma_f32_32x32x16_bf16 v[2:17], v[102:105], v[90:93], v[2:17]
	v_exp_f32_e32 v224, v68
	v_mfma_f32_32x32x16_bf16 v[2:17], v[106:109], v[176:179], v[2:17]
	v_exp_f32_e32 v225, v69
	ds_read_b64_tr_b16 v[90:91], v184 offset:0x400
	ds_read_b64_tr_b16 v[92:93], v184 offset:0xc00
	ds_read_b64_tr_b16 v[110:111], v184 offset:0x1400
	ds_read_b64_tr_b16 v[112:113], v184 offset:0x1c00
	ds_read_b64_tr_b16 v[176:177], v184 offset:0x2400
	ds_read_b64_tr_b16 v[178:179], v184 offset:0x2c00
	ds_read_b64_tr_b16 v[208:209], v184 offset:0x3400
	ds_read_b64_tr_b16 v[210:211], v184 offset:0x3c00
	s_waitcnt lgkmcnt(8)
	v_mfma_f32_32x32x16_bf16 v[18:33], v[94:97], v[192:195], v[18:33]
	v_exp_f32_e32 v226, v70
	v_exp_f32_e32 v84, v116
	v_exp_f32_e32 v85, v117
	v_exp_f32_e32 v86, v118
	v_exp_f32_e32 v87, v119
	v_mfma_f32_32x32x16_bf16 v[18:33], v[98:101], v[196:199], v[18:33]
	v_exp_f32_e32 v227, v71
	v_mfma_f32_32x32x16_bf16 v[18:33], v[102:105], v[200:203], v[18:33]
	v_exp_f32_e32 v228, v72
	v_mfma_f32_32x32x16_bf16 v[18:33], v[106:109], v[204:207], v[18:33]
	v_exp_f32_e32 v229, v73
	ds_read_b64_tr_b16 v[114:115], v184 offset:0x600
	ds_read_b64_tr_b16 v[116:117], v184 offset:0xe00
	ds_read_b64_tr_b16 v[192:193], v184 offset:0x1600
	ds_read_b64_tr_b16 v[194:195], v184 offset:0x1e00
	ds_read_b64_tr_b16 v[196:197], v184 offset:0x2600
	ds_read_b64_tr_b16 v[198:199], v184 offset:0x2e00
	ds_read_b64_tr_b16 v[200:201], v184 offset:0x3600
	ds_read_b64_tr_b16 v[202:203], v184 offset:0x3e00
	s_waitcnt lgkmcnt(8)
	v_mfma_f32_32x32x16_bf16 v[34:49], v[94:97], v[90:93], v[34:49]
	v_exp_f32_e32 v230, v74
	v_exp_f32_e32 v90, v120
	v_exp_f32_e32 v89, v121
	v_exp_f32_e32 v92, v122
	v_exp_f32_e32 v91, v123
	v_mfma_f32_32x32x16_bf16 v[34:49], v[98:101], v[110:113], v[34:49]
	v_exp_f32_e32 v231, v75
	v_mfma_f32_32x32x16_bf16 v[34:49], v[102:105], v[176:179], v[34:49]
	v_exp_f32_e32 v232, v76
	v_mfma_f32_32x32x16_bf16 v[34:49], v[106:109], v[208:211], v[34:49]
	v_exp_f32_e32 v233, v77
	s_waitcnt lgkmcnt(0)
	v_mfma_f32_32x32x16_bf16 v[50:65], v[94:97], v[114:117], v[50:65]
	v_exp_f32_e32 v234, v78
	v_exp_f32_e32 v94, v124
	v_exp_f32_e32 v93, v125
	v_exp_f32_e32 v95, v126
	v_exp_f32_e32 v151, v127
	v_mfma_f32_32x32x16_bf16 v[50:65], v[98:101], v[192:195], v[50:65]
	v_exp_f32_e32 v235, v79
	v_mfma_f32_32x32x16_bf16 v[50:65], v[102:105], v[196:199], v[50:65]
	v_exp_f32_e32 v236, v80
	v_mfma_f32_32x32x16_bf16 v[50:65], v[106:109], v[200:203], v[50:65]
	v_exp_f32_e32 v237, v81
	s_waitcnt vmcnt(0)
	s_add_u32 s4, s4, 0x180000
	s_addc_u32 s5, s5, 0
	s_add_i32 s16, s16, 2
	s_and_b64 vcc, exec, s[0:1]
	s_waitcnt vmcnt(0)
	s_barrier
	s_cbranch_vccnz .LBB0_911

.LBB0_909:
	v_lshl_add_u64 v[178:179], s[4:5], 0, v[172:173]
	s_mov_b32 m0, s30
	v_lshl_add_u64 v[96:97], v[178:179], 0, s[8:9]
	v_lshl_add_u64 v[176:177], s[4:5], 0, v[174:175]
	global_load_lds_dwordx4 v[96:97], off
	v_lshl_add_u64 v[96:97], v[176:177], 0, s[8:9]
	s_mov_b32 m0, s33
	s_nop 0
	global_load_lds_dwordx4 v[96:97], off
	ds_read_b128 v[96:99], v188 offset:32768
	ds_read_b128 v[100:103], v188 offset:36864
	ds_read_b128 v[192:195], v189 offset:32768
	ds_read_b128 v[196:199], v189 offset:36864
	ds_read_b128 v[200:203], v190 offset:32768
	ds_read_b128 v[204:207], v190 offset:36864
	ds_read_b128 v[208:211], v191 offset:32768
	ds_read_b128 v[212:215], v191 offset:36864
	s_waitcnt lgkmcnt(0)
	v_mfma_f32_32x32x16_bf16 v[112:127], v[96:99], v[128:131], 0
	v_mfma_f32_32x32x16_bf16 v[96:111], v[100:103], v[128:131], 0
	v_mfma_f32_32x32x16_bf16 v[112:127], v[192:195], v[132:135], v[112:127]
	v_mfma_f32_32x32x16_bf16 v[96:111], v[196:199], v[132:135], v[96:111]
	v_add_f32_e32 v67, v88, v1
	v_cvt_pk_bf16_f32 v66, v88, v1
	v_add_f32_e32 v1, v222, v223
	v_add_f32_e32 v67, v67, v82
	v_mfma_f32_32x32x16_bf16 v[112:127], v[200:203], v[136:139], v[112:127]
	v_add_f32_e32 v1, v1, v224
	v_add_f32_e32 v67, v67, v83
	v_cvt_pk_bf16_f32 v68, v84, v85
	v_add_f32_e32 v1, v1, v225
	v_add_f32_e32 v67, v67, v84
	v_cvt_pk_bf16_f32 v69, v86, v87
	v_add_f32_e32 v1, v1, v226
	v_add_f32_e32 v67, v67, v85
	v_mfma_f32_32x32x16_bf16 v[96:111], v[204:207], v[136:139], v[96:111]
	v_add_f32_e32 v1, v1, v227
	v_add_f32_e32 v67, v67, v86
	v_permlane32_swap_b32_e32 v66, v68
	v_add_f32_e32 v1, v1, v228
	v_add_f32_e32 v67, v67, v87
	v_add_f32_e32 v1, v1, v229
	v_add_f32_e32 v67, v67, v90
	v_add_f32_e32 v1, v1, v230
	v_add_f32_e32 v67, v67, v89
	v_add_f32_e32 v1, v1, v231
	v_add_f32_e32 v67, v67, v92
	v_add_f32_e32 v1, v1, v232
	v_add_f32_e32 v67, v67, v91
	v_add_f32_e32 v1, v1, v233
	v_add_f32_e32 v67, v67, v94
	v_add_f32_e32 v1, v1, v234
	v_add_f32_e32 v67, v67, v93
	v_add_f32_e32 v1, v1, v235
	v_add_f32_e32 v67, v67, v95
	v_add_f32_e32 v1, v1, v236
	v_add_f32_e32 v67, v67, v151
	v_add_f32_e32 v1, v1, v237
	v_add_f32_e32 v1, v67, v1
	v_mov_b32_e32 v70, v1
	s_nop 1
	v_permlane32_swap_b32_e32 v1, v70
	v_cvt_pk_bf16_f32 v67, v82, v83
	s_nop 1
	v_permlane32_swap_b32_e32 v67, v69
	v_mfma_f32_32x32x16_bf16 v[112:127], v[208:211], v[140:143], v[112:127]
	v_cvt_pk_bf16_f32 v72, v90, v89
	v_cvt_pk_bf16_f32 v73, v92, v91
	v_cvt_pk_bf16_f32 v74, v94, v93
	v_cvt_pk_bf16_f32 v75, v95, v151
	v_cvt_pk_bf16_f32 v76, v222, v223
	v_cvt_pk_bf16_f32 v77, v224, v225
	v_cvt_pk_bf16_f32 v78, v226, v227
	v_mfma_f32_32x32x16_bf16 v[96:111], v[212:215], v[140:143], v[96:111]
	v_cvt_pk_bf16_f32 v79, v228, v229
	v_cvt_pk_bf16_f32 v80, v230, v231
	v_cvt_pk_bf16_f32 v81, v232, v233
	v_cvt_pk_bf16_f32 v82, v234, v235
	v_cvt_pk_bf16_f32 v83, v236, v237
	v_permlane32_swap_b32_e32 v72, v74
	v_permlane32_swap_b32_e32 v73, v75
	v_permlane32_swap_b32_e32 v76, v78
	v_permlane32_swap_b32_e32 v77, v79
	v_permlane32_swap_b32_e32 v80, v82
	v_permlane32_swap_b32_e32 v81, v83
	ds_read_b64_tr_b16 v[84:85], v185 offset:0
	ds_read_b64_tr_b16 v[86:87], v185 offset:0x800
	ds_read_b64_tr_b16 v[88:89], v185 offset:0x1000
	ds_read_b64_tr_b16 v[90:91], v185 offset:0x1800
	ds_read_b64_tr_b16 v[92:93], v185 offset:0x2000
	ds_read_b64_tr_b16 v[94:95], v185 offset:0x2800
	ds_read_b64_tr_b16 v[192:193], v185 offset:0x3000
	ds_read_b64_tr_b16 v[194:195], v185 offset:0x3800
	ds_read_b64_tr_b16 v[196:197], v185 offset:0x200
	ds_read_b64_tr_b16 v[198:199], v185 offset:0xa00
	ds_read_b64_tr_b16 v[200:201], v185 offset:0x1200
	ds_read_b64_tr_b16 v[202:203], v185 offset:0x1a00
	ds_read_b64_tr_b16 v[204:205], v185 offset:0x2200
	ds_read_b64_tr_b16 v[206:207], v185 offset:0x2a00
	ds_read_b64_tr_b16 v[208:209], v185 offset:0x3200
	ds_read_b64_tr_b16 v[210:211], v185 offset:0x3a00
	s_waitcnt lgkmcnt(8)
	s_nop 0
	v_mfma_f32_32x32x16_bf16 v[2:17], v[66:69], v[84:87], v[2:17]
	v_exp_f32_e32 v238, v112
	v_exp_f32_e32 v239, v113
	v_mfma_f32_32x32x16_bf16 v[2:17], v[72:75], v[88:91], v[2:17]
	v_exp_f32_e32 v240, v114
	v_exp_f32_e32 v241, v115
	v_mfma_f32_32x32x16_bf16 v[2:17], v[76:79], v[92:95], v[2:17]
	v_exp_f32_e32 v244, v116
	v_exp_f32_e32 v245, v117
	v_mfma_f32_32x32x16_bf16 v[2:17], v[80:83], v[192:195], v[2:17]
	v_exp_f32_e32 v246, v118
	v_exp_f32_e32 v247, v119
	ds_read_b64_tr_b16 v[84:85], v185 offset:0x400
	ds_read_b64_tr_b16 v[86:87], v185 offset:0xc00
	ds_read_b64_tr_b16 v[88:89], v185 offset:0x1400
	ds_read_b64_tr_b16 v[90:91], v185 offset:0x1c00
	ds_read_b64_tr_b16 v[92:93], v185 offset:0x2400
	ds_read_b64_tr_b16 v[94:95], v185 offset:0x2c00
	ds_read_b64_tr_b16 v[192:193], v185 offset:0x3400
	ds_read_b64_tr_b16 v[194:195], v185 offset:0x3c00
	s_waitcnt lgkmcnt(8)
	v_mfma_f32_32x32x16_bf16 v[18:33], v[66:69], v[196:199], v[18:33]
	v_exp_f32_e32 v248, v120
	v_exp_f32_e32 v249, v121
	v_mfma_f32_32x32x16_bf16 v[18:33], v[72:75], v[200:203], v[18:33]
	v_exp_f32_e32 v250, v122
	v_exp_f32_e32 v251, v123
	v_mfma_f32_32x32x16_bf16 v[18:33], v[76:79], v[204:207], v[18:33]
	v_exp_f32_e32 v252, v124
	v_exp_f32_e32 v253, v125
	v_mfma_f32_32x32x16_bf16 v[18:33], v[80:83], v[208:211], v[18:33]
	v_exp_f32_e32 v254, v126
	v_exp_f32_e32 v255, v127
	ds_read_b64_tr_b16 v[196:197], v185 offset:0x600
	ds_read_b64_tr_b16 v[198:199], v185 offset:0xe00
	ds_read_b64_tr_b16 v[200:201], v185 offset:0x1600
	ds_read_b64_tr_b16 v[202:203], v185 offset:0x1e00
	ds_read_b64_tr_b16 v[204:205], v185 offset:0x2600
	ds_read_b64_tr_b16 v[206:207], v185 offset:0x2e00
	ds_read_b64_tr_b16 v[208:209], v185 offset:0x3600
	ds_read_b64_tr_b16 v[210:211], v185 offset:0x3e00
	s_waitcnt lgkmcnt(8)
	v_mfma_f32_32x32x16_bf16 v[34:49], v[66:69], v[84:87], v[34:49]
	v_exp_f32_e32 v222, v96
	v_exp_f32_e32 v223, v97
	v_mfma_f32_32x32x16_bf16 v[34:49], v[72:75], v[88:91], v[34:49]
	v_exp_f32_e32 v224, v98
	v_exp_f32_e32 v225, v99
	v_mfma_f32_32x32x16_bf16 v[34:49], v[76:79], v[92:95], v[34:49]
	v_exp_f32_e32 v226, v100
	v_exp_f32_e32 v227, v101
	v_mfma_f32_32x32x16_bf16 v[34:49], v[80:83], v[192:195], v[34:49]
	v_exp_f32_e32 v228, v102
	v_exp_f32_e32 v229, v103
	s_waitcnt lgkmcnt(0)
	v_mfma_f32_32x32x16_bf16 v[50:65], v[66:69], v[196:199], v[50:65]
	v_exp_f32_e32 v230, v104
	v_exp_f32_e32 v231, v105
	v_mfma_f32_32x32x16_bf16 v[50:65], v[72:75], v[200:203], v[50:65]
	v_exp_f32_e32 v232, v106
	v_exp_f32_e32 v233, v107
	v_mfma_f32_32x32x16_bf16 v[50:65], v[76:79], v[204:207], v[50:65]
	v_exp_f32_e32 v234, v108
	v_exp_f32_e32 v235, v109
	v_mfma_f32_32x32x16_bf16 v[50:65], v[80:83], v[208:211], v[50:65]
	v_exp_f32_e32 v236, v110
	v_exp_f32_e32 v237, v111
	s_waitcnt vmcnt(0)
	s_cmp_ge_u32 s16, s11
	s_cselect_b64 s[0:1], -1, 0
	s_and_b64 vcc, exec, s[0:1]
	s_waitcnt vmcnt(0)
	s_barrier
	s_cbranch_vccnz .LBB0_906
	s_mov_b64 s[18:19], 0x15c81800
	v_lshl_add_u64 v[66:67], v[180:181], 0, s[18:19]
	s_mov_b32 m0, s31
	s_nop 0
	global_load_lds_dwordx4 v[66:67], off
	s_branch .LBB0_906

.LBB0_2318:
	s_lshl_b32 s0, s30, 1
	s_and_b32 s24, s0, 0x700
	s_ashr_i32 s0, s30, 10
	s_ashr_i32 s1, s0, 31
	s_lshl_b64 s[46:47], s[0:1], 14
	s_lshl_b32 s1, s30, 8
	s_and_b32 s1, s1, 0x3f00
	s_or_b32 s46, s46, s1
	s_bfe_u32 s23, s30, 0x40006
	s_mul_i32 s4, s47, 0x3000
	s_mul_hi_u32 s21, s46, 0x3000
	s_lshl_b32 s52, s23, 7
	s_lshl_b32 s1, s0, 8
	s_add_i32 s21, s21, s4
	s_mul_i32 s4, s46, 0x3000
	v_readlane_b32 s40, v242, 17
	v_readlane_b32 s41, v242, 18
	s_add_u32 s4, s40, s4
	s_addc_u32 s21, s41, s21
	s_add_u32 s4, s4, s52
	s_addc_u32 s21, s21, 0
	s_add_u32 s28, s4, 0x1000
	s_addc_u32 s29, s21, 0
	s_mul_i32 s4, s0, 0x300000
	s_mul_hi_i32 s1, s1, 0x3000
	s_add_u32 s4, s40, s4
	s_addc_u32 s21, s41, s1
	s_add_u32 s34, s4, s52
	s_addc_u32 s35, s21, 0
	s_mul_i32 s58, s0, 0xc000000
	s_mul_hi_i32 s25, s0, 0xc000000
	s_add_u32 s0, s40, s58
	s_addc_u32 s1, s41, s25
	s_add_u32 s0, s0, s52
	s_addc_u32 s1, s1, 0
	s_and_b32 s31, s52, 0x700
	s_add_u32 s61, s4, s31
	s_addc_u32 s62, s21, 0
	s_add_u32 s40, s61, 0x18002000
	v_readfirstlane_b32 s33, v0
	s_addc_u32 s41, s62, 0
	s_lshr_b32 s31, s33, 6
	s_lshl_b32 s4, s31, 5
	v_or_b32_e32 v4, s4, v165
	v_mov_b64_e32 v[2:3], s[28:29]
	v_mad_u64_u32 v[2:3], s[28:29], v4, s20, v[2:3]
	v_lshl_add_u64 v[2:3], v[2:3], 0, v[132:133]
	global_load_dwordx4 v[114:117], v[2:3], off
	global_load_dwordx4 v[118:121], v[2:3], off offset:32
	global_load_dwordx4 v[122:125], v[2:3], off offset:64
	global_load_dwordx4 v[126:129], v[2:3], off offset:96
	s_andn2_b32 s33, s33, 63
	s_ashr_i32 s21, s33, 4
	s_and_b32 s28, s21, -16
	s_lshr_b32 s21, s21, 1
	s_and_b32 s21, s21, 4
	v_or_b32_e32 v2, s33, v166
	s_or_b32 s60, s28, s21
	s_add_i32 s21, s33, 0x200
	v_ashrrev_i32_e32 v3, 31, v2
	s_ashr_i32 s21, s21, 4
	v_lshrrev_b32_e32 v3, 29, v3
	s_and_b32 s28, s21, -16
	s_lshr_b32 s21, s21, 1
	v_add_u32_e32 v3, v2, v3
	s_and_b32 s21, s21, 4
	v_ashrrev_i32_e32 v5, 3, v3
	v_and_b32_e32 v3, 0x1ffffff8, v3
	s_or_b32 s59, s28, s21
	v_sub_u32_e32 v3, v2, v3
	v_lshrrev_b32_e32 v4, 1, v5
	v_and_b32_e32 v137, 0x60, v2
	v_or_b32_e32 v2, s60, v163
	v_or_b32_e32 v6, s59, v163
	v_bitop3_b32 v3, v4, v3, 7 bitop3:0x6c
	v_or_b32_e32 v4, v137, v162
	v_mul_lo_u32 v2, v2, s22
	v_mul_lo_u32 v6, v6, s22
	v_mul_lo_u32 v5, v5, s22
	v_or_b32_e32 v2, v2, v4
	v_or_b32_e32 v4, v6, v4
	v_lshl_add_u32 v6, v3, 3, v5
	v_ashrrev_i32_e32 v7, 31, v6
	v_lshlrev_b64 v[150:151], 1, v[6:7]
	s_lshl_b32 s21, s31, 10
	v_lshl_add_u64 v[98:99], s[34:35], 0, v[150:151]
	s_add_i32 s34, s21, 0
	s_add_i32 s35, s34, 0x8000
	v_ashrrev_i32_e32 v3, 31, v2
	v_lshl_add_u64 v[6:7], v[98:99], 0, s[6:7]
	s_mov_b32 m0, s35
	v_lshlrev_b64 v[152:153], 1, v[2:3]
	v_ashrrev_i32_e32 v5, 31, v4
	global_load_lds_dwordx4 v[6:7], off
	v_lshl_add_u64 v[2:3], s[40:41], 0, v[152:153]
	s_mov_b32 m0, s34
	v_lshlrev_b64 v[154:155], 1, v[4:5]
	s_add_i32 s54, s34, 0x2000
	global_load_lds_dwordx4 v[2:3], off
	v_lshl_add_u64 v[2:3], s[40:41], 0, v[154:155]
	s_mov_b32 m0, s54
	s_add_i32 s55, s34, 0xa000
	global_load_lds_dwordx4 v[2:3], off
	v_lshl_add_u64 v[2:3], v[98:99], 0, s[8:9]
	s_mov_b32 m0, s55
	s_waitcnt vmcnt(0)
	s_waitcnt vmcnt(0) lgkmcnt(0)
	s_barrier
	global_load_lds_dwordx4 v[2:3], off
	ds_read_b128 v[2:5], v172 offset:32768
	ds_read_b128 v[18:21], v172 offset:36864
	s_waitcnt lgkmcnt(0)
	v_mfma_f32_32x32x16_bf16 v[2:17], v[2:5], v[114:117], 0
	ds_read_b128 v[22:25], v173 offset:32768
	ds_read_b128 v[34:37], v173 offset:36864
	s_add_u32 s28, s61, 0x180c2000
	v_lshl_add_u64 v[30:31], v[98:99], 0, s[12:13]
	s_mov_b32 m0, s35
	s_addc_u32 s29, s62, 0
	s_add_i32 s56, s34, 0x4000
	s_add_i32 s57, s34, 0x6000
	s_waitcnt lgkmcnt(0)
	v_mfma_f32_32x32x16_bf16 v[2:17], v[22:25], v[118:121], v[2:17]
	ds_read_b128 v[22:25], v174 offset:32768
	ds_read_b128 v[38:41], v174 offset:36864
	ds_read_b128 v[26:29], v175 offset:32768
	ds_read_b128 v[42:45], v175 offset:36864
	s_waitcnt vmcnt(0)
	s_waitcnt vmcnt(0) lgkmcnt(0)
	s_barrier
	global_load_lds_dwordx4 v[30:31], off
	v_mfma_f32_32x32x16_bf16 v[2:17], v[22:25], v[122:125], v[2:17]
	v_lshl_add_u64 v[22:23], s[28:29], 0, v[152:153]
	s_mov_b32 m0, s56
	s_mov_b32 s53, s5
	global_load_lds_dwordx4 v[22:23], off
	v_lshl_add_u64 v[22:23], s[28:29], 0, v[154:155]
	s_mov_b32 m0, s57
	v_mfma_f32_32x32x16_bf16 v[2:17], v[26:29], v[126:129], v[2:17]
	global_load_lds_dwordx4 v[22:23], off
	v_mfma_f32_32x32x16_bf16 v[18:33], v[18:21], v[114:117], 0
	s_nop 9
	v_exp_f32_e32 v54, v2
	v_exp_f32_e32 v55, v3
	v_exp_f32_e32 v56, v4
	v_exp_f32_e32 v57, v5
	v_exp_f32_e32 v58, v6
	v_exp_f32_e32 v59, v7
	v_exp_f32_e32 v60, v8
	v_mfma_f32_32x32x16_bf16 v[18:33], v[34:37], v[118:121], v[18:33]
	v_exp_f32_e32 v61, v9
	v_exp_f32_e32 v62, v10
	v_exp_f32_e32 v63, v11
	v_exp_f32_e32 v64, v12
	v_exp_f32_e32 v65, v13
	v_exp_f32_e32 v102, v14
	v_exp_f32_e32 v103, v15
	v_mfma_f32_32x32x16_bf16 v[18:33], v[38:41], v[122:125], v[18:33]
	v_exp_f32_e32 v104, v16
	v_exp_f32_e32 v105, v17
	ds_read_b128 v[2:5], v172 offset:40960
	ds_read_b128 v[6:9], v172 offset:45056
	ds_read_b128 v[10:13], v173 offset:40960
	ds_read_b128 v[14:17], v173 offset:45056
	ds_read_b128 v[34:37], v174 offset:40960
	ds_read_b128 v[38:41], v174 offset:45056
	ds_read_b128 v[46:49], v175 offset:40960
	ds_read_b128 v[50:53], v175 offset:45056
	v_mfma_f32_32x32x16_bf16 v[18:33], v[42:45], v[126:129], v[18:33]
	s_waitcnt lgkmcnt(0)
	v_mfma_f32_32x32x16_bf16 v[66:81], v[6:9], v[114:117], 0
	v_mfma_f32_32x32x16_bf16 v[82:97], v[2:5], v[114:117], 0
	s_nop 8
	v_exp_f32_e32 v2, v18
	v_exp_f32_e32 v3, v19
	v_exp_f32_e32 v4, v20
	v_exp_f32_e32 v5, v21
	v_exp_f32_e32 v18, v22
	v_exp_f32_e32 v19, v23
	v_exp_f32_e32 v20, v24
	v_exp_f32_e32 v21, v25
	v_mfma_f32_32x32x16_bf16 v[66:81], v[14:17], v[118:121], v[66:81]
	v_exp_f32_e32 v6, v26
	v_exp_f32_e32 v7, v27
	v_exp_f32_e32 v8, v28
	v_exp_f32_e32 v9, v29
	v_mfma_f32_32x32x16_bf16 v[82:97], v[10:13], v[118:121], v[82:97]
	v_exp_f32_e32 v10, v30
	v_exp_f32_e32 v11, v31
	v_exp_f32_e32 v12, v32
	v_exp_f32_e32 v13, v33
	v_add_f32_e32 v14, v54, v55
	v_add_f32_e32 v15, v2, v3
	v_mfma_f32_32x32x16_bf16 v[66:81], v[38:41], v[122:125], v[66:81]
	v_add_f32_e32 v14, v14, v56
	v_add_f32_e32 v15, v15, v4
	v_cvt_pk_bf16_f32 v54, v54, v55
	v_add_f32_e32 v14, v14, v57
	v_add_f32_e32 v15, v15, v5
	v_cvt_pk_bf16_f32 v55, v56, v57
	v_add_f32_e32 v14, v14, v58
	v_add_f32_e32 v15, v15, v18
	v_cvt_pk_bf16_f32 v56, v58, v59
	v_add_f32_e32 v14, v14, v59
	v_add_f32_e32 v15, v15, v19
	v_cvt_pk_bf16_f32 v57, v60, v61
	v_add_f32_e32 v14, v14, v60
	v_add_f32_e32 v15, v15, v20
	s_nop 0
	v_permlane32_swap_b32_e32 v54, v56
	v_add_f32_e32 v14, v14, v61
	v_add_f32_e32 v15, v15, v21
	v_permlane32_swap_b32_e32 v55, v57
	v_add_f32_e32 v14, v14, v62
	v_add_f32_e32 v15, v15, v6
	v_mfma_f32_32x32x16_bf16 v[82:97], v[34:37], v[122:125], v[82:97]
	v_add_f32_e32 v14, v14, v63
	v_add_f32_e32 v15, v15, v7
	s_nop 0
	v_add_f32_e32 v14, v14, v64
	v_add_f32_e32 v15, v15, v8
	s_nop 0
	v_add_f32_e32 v14, v14, v65
	v_add_f32_e32 v15, v15, v9
	s_nop 0
	v_add_f32_e32 v14, v14, v102
	v_add_f32_e32 v15, v15, v10
	s_nop 0
	v_add_f32_e32 v14, v14, v103
	v_add_f32_e32 v15, v15, v11
	s_nop 0
	v_add_f32_e32 v14, v14, v104
	v_add_f32_e32 v15, v15, v12
	s_nop 0
	v_add_f32_e32 v14, v14, v105
	v_add_f32_e32 v15, v15, v13
	s_nop 0
	v_add_f32_e32 v14, v14, v15
	v_mov_b32_e32 v15, v14
	s_nop 1
	v_permlane32_swap_b32_e32 v14, v15
	v_add_f32_e32 v14, v14, v15
	v_add_f32_e32 v135, 0, v14
	v_mfma_f32_32x32x16_bf16 v[66:81], v[50:53], v[126:129], v[66:81]
	v_cvt_pk_bf16_f32 v100, v62, v63
	v_cvt_pk_bf16_f32 v101, v64, v65
	v_cvt_pk_bf16_f32 v102, v102, v103
	v_cvt_pk_bf16_f32 v103, v104, v105
	v_cvt_pk_bf16_f32 v104, v2, v3
	v_cvt_pk_bf16_f32 v105, v4, v5
	v_cvt_pk_bf16_f32 v106, v18, v19
	v_cvt_pk_bf16_f32 v107, v20, v21
	v_cvt_pk_bf16_f32 v108, v6, v7
	v_cvt_pk_bf16_f32 v109, v8, v9
	v_cvt_pk_bf16_f32 v110, v10, v11
	v_cvt_pk_bf16_f32 v111, v12, v13
	v_mfma_f32_32x32x16_bf16 v[82:97], v[46:49], v[126:129], v[82:97]
	v_permlane32_swap_b32_e32 v100, v102
	v_permlane32_swap_b32_e32 v101, v103
	v_permlane32_swap_b32_e32 v104, v106
	v_permlane32_swap_b32_e32 v105, v107
	v_permlane32_swap_b32_e32 v108, v110
	v_permlane32_swap_b32_e32 v109, v111
	ds_read_b64_tr_b16 v[2:3], v168 offset:0
	ds_read_b64_tr_b16 v[4:5], v168 offset:0x800
	ds_read_b64_tr_b16 v[18:19], v168 offset:0x1000
	ds_read_b64_tr_b16 v[20:21], v168 offset:0x1800
	ds_read_b64_tr_b16 v[22:23], v168 offset:0x2000
	ds_read_b64_tr_b16 v[24:25], v168 offset:0x2800
	ds_read_b64_tr_b16 v[26:27], v168 offset:0x3000
	ds_read_b64_tr_b16 v[28:29], v168 offset:0x3800
	ds_read_b64_tr_b16 v[30:31], v168 offset:0x200
	ds_read_b64_tr_b16 v[32:33], v168 offset:0xa00
	ds_read_b64_tr_b16 v[34:35], v168 offset:0x1200
	ds_read_b64_tr_b16 v[36:37], v168 offset:0x1a00
	ds_read_b64_tr_b16 v[38:39], v168 offset:0x2200
	ds_read_b64_tr_b16 v[40:41], v168 offset:0x2a00
	ds_read_b64_tr_b16 v[42:43], v168 offset:0x3200
	ds_read_b64_tr_b16 v[44:45], v168 offset:0x3a00
	s_waitcnt lgkmcnt(8)
	s_nop 0
	v_mfma_f32_32x32x16_bf16 v[2:17], v[54:57], v[2:5], 0
	s_nop 3
	v_exp_f32_e32 v139, v82
	v_exp_f32_e32 v141, v83
	v_exp_f32_e32 v143, v84
	v_exp_f32_e32 v145, v85
	v_mfma_f32_32x32x16_bf16 v[2:17], v[100:103], v[18:21], v[2:17]
	v_mfma_f32_32x32x16_bf16 v[2:17], v[104:107], v[22:25], v[2:17]
	v_mfma_f32_32x32x16_bf16 v[2:17], v[108:111], v[26:29], v[2:17]
	ds_read_b64_tr_b16 v[46:47], v168 offset:0x400
	ds_read_b64_tr_b16 v[48:49], v168 offset:0xc00
	ds_read_b64_tr_b16 v[50:51], v168 offset:0x1400
	ds_read_b64_tr_b16 v[52:53], v168 offset:0x1c00
	ds_read_b64_tr_b16 v[58:59], v168 offset:0x2400
	ds_read_b64_tr_b16 v[60:61], v168 offset:0x2c00
	ds_read_b64_tr_b16 v[62:63], v168 offset:0x3400
	ds_read_b64_tr_b16 v[64:65], v168 offset:0x3c00
	s_waitcnt lgkmcnt(8)
	v_mfma_f32_32x32x16_bf16 v[18:33], v[54:57], v[30:33], 0
	v_exp_f32_e32 v147, v86
	v_exp_f32_e32 v149, v87
	v_exp_f32_e32 v196, v88
	v_exp_f32_e32 v197, v89
	v_mfma_f32_32x32x16_bf16 v[18:33], v[100:103], v[34:37], v[18:33]
	v_mfma_f32_32x32x16_bf16 v[18:33], v[104:107], v[38:41], v[18:33]
	v_mfma_f32_32x32x16_bf16 v[18:33], v[108:111], v[42:45], v[18:33]
	ds_read_b64_tr_b16 v[82:83], v168 offset:0x600
	ds_read_b64_tr_b16 v[84:85], v168 offset:0xe00
	ds_read_b64_tr_b16 v[86:87], v168 offset:0x1600
	ds_read_b64_tr_b16 v[88:89], v168 offset:0x1e00
	ds_read_b64_tr_b16 v[156:157], v168 offset:0x2600
	ds_read_b64_tr_b16 v[158:159], v168 offset:0x2e00
	ds_read_b64_tr_b16 v[176:177], v168 offset:0x3600
	ds_read_b64_tr_b16 v[178:179], v168 offset:0x3e00
	s_waitcnt lgkmcnt(8)
	v_mfma_f32_32x32x16_bf16 v[34:49], v[54:57], v[46:49], 0
	v_exp_f32_e32 v198, v90
	v_exp_f32_e32 v199, v91
	v_exp_f32_e32 v200, v92
	v_exp_f32_e32 v201, v93
	v_mfma_f32_32x32x16_bf16 v[34:49], v[100:103], v[50:53], v[34:49]
	v_mfma_f32_32x32x16_bf16 v[34:49], v[104:107], v[58:61], v[34:49]
	v_mfma_f32_32x32x16_bf16 v[34:49], v[108:111], v[62:65], v[34:49]
	s_waitcnt lgkmcnt(0)
	v_mfma_f32_32x32x16_bf16 v[50:65], v[54:57], v[82:85], 0
	v_exp_f32_e32 v202, v94
	v_exp_f32_e32 v203, v95
	v_exp_f32_e32 v204, v96
	v_exp_f32_e32 v205, v97
	v_mfma_f32_32x32x16_bf16 v[50:65], v[100:103], v[86:89], v[50:65]
	v_mfma_f32_32x32x16_bf16 v[50:65], v[104:107], v[156:159], v[50:65]
	v_mfma_f32_32x32x16_bf16 v[50:65], v[108:111], v[176:179], v[50:65]
	s_add_u32 s28, s61, 0x18182000
	s_mov_b32 m0, s55
	v_lshl_add_u64 v[82:83], v[98:99], 0, s[16:17]
	s_addc_u32 s29, s62, 0
	s_waitcnt vmcnt(0)
	s_waitcnt vmcnt(0)
	s_barrier
	global_load_lds_dwordx4 v[82:83], off
	v_lshl_add_u64 v[82:83], s[28:29], 0, v[152:153]
	s_mov_b32 m0, s34
	v_lshl_add_u64 v[90:91], s[0:1], 0, v[150:151]
	global_load_lds_dwordx4 v[82:83], off
	v_lshl_add_u64 v[82:83], s[28:29], 0, v[154:155]
	s_mov_b32 m0, s54
	v_lshl_add_u64 v[160:161], v[90:91], 0, s[14:15]
	global_load_lds_dwordx4 v[82:83], off
	ds_read_b128 v[82:85], v172 offset:32768
	ds_read_b128 v[86:89], v172 offset:36864
	ds_read_b128 v[156:159], v173 offset:32768
	ds_read_b128 v[176:179], v173 offset:36864
	ds_read_b128 v[180:183], v174 offset:32768
	ds_read_b128 v[184:187], v174 offset:36864
	ds_read_b128 v[188:191], v175 offset:32768
	ds_read_b128 v[192:195], v175 offset:36864
	s_waitcnt lgkmcnt(0)
	v_mfma_f32_32x32x16_bf16 v[98:113], v[82:85], v[114:117], 0
	v_exp_f32_e32 v206, v66
	v_exp_f32_e32 v207, v67
	v_exp_f32_e32 v208, v68
	v_exp_f32_e32 v209, v69
	v_exp_f32_e32 v210, v70
	v_exp_f32_e32 v211, v71
	v_exp_f32_e32 v212, v72
	v_exp_f32_e32 v213, v73
	v_mfma_f32_32x32x16_bf16 v[82:97], v[86:89], v[114:117], 0
	v_exp_f32_e32 v81, v81
	v_mfma_f32_32x32x16_bf16 v[98:113], v[156:159], v[118:121], v[98:113]
	v_exp_f32_e32 v157, v74
	v_exp_f32_e32 v159, v75
	v_exp_f32_e32 v214, v76
	v_exp_f32_e32 v215, v77
	v_exp_f32_e32 v216, v78
	v_exp_f32_e32 v217, v79
	v_exp_f32_e32 v218, v80
	v_mfma_f32_32x32x16_bf16 v[82:97], v[176:179], v[118:121], v[82:97]
	v_add_f32_e32 v66, v139, v141
	v_add_f32_e32 v67, v206, v207
	v_cvt_pk_bf16_f32 v68, v147, v149
	v_add_f32_e32 v66, v66, v143
	v_add_f32_e32 v67, v67, v208
	v_cvt_pk_bf16_f32 v69, v196, v197
	v_add_f32_e32 v66, v66, v145
	v_add_f32_e32 v67, v67, v209
	v_mfma_f32_32x32x16_bf16 v[98:113], v[180:183], v[122:125], v[98:113]
	v_add_f32_e32 v66, v66, v147
	v_add_f32_e32 v67, v67, v210
	s_nop 0
	v_add_f32_e32 v66, v66, v149
	v_add_f32_e32 v67, v67, v211
	s_nop 0
	v_add_f32_e32 v66, v66, v196
	v_add_f32_e32 v67, v67, v212
	v_mfma_f32_32x32x16_bf16 v[82:97], v[184:187], v[122:125], v[82:97]
	v_add_f32_e32 v66, v66, v197
	v_add_f32_e32 v67, v67, v213
	s_nop 0
	v_add_f32_e32 v66, v66, v198
	v_add_f32_e32 v67, v67, v157
	s_nop 0
	v_add_f32_e32 v66, v66, v199
	v_add_f32_e32 v67, v67, v159
	s_nop 0
	v_add_f32_e32 v66, v66, v200
	v_add_f32_e32 v67, v67, v214
	s_nop 0
	v_add_f32_e32 v66, v66, v201
	v_add_f32_e32 v67, v67, v215
	s_nop 0
	v_add_f32_e32 v66, v66, v202
	v_add_f32_e32 v67, v67, v216
	s_nop 0
	v_add_f32_e32 v66, v66, v203
	v_add_f32_e32 v67, v67, v217
	s_nop 0
	v_add_f32_e32 v66, v66, v204
	v_add_f32_e32 v67, v67, v218
	s_nop 0
	v_add_f32_e32 v66, v66, v205
	v_add_f32_e32 v67, v67, v81
	s_nop 0
	v_add_f32_e32 v156, v66, v67
	v_cvt_pk_bf16_f32 v66, v139, v141
	v_cvt_pk_bf16_f32 v67, v143, v145
	v_mov_b32_e32 v158, v156
	v_permlane32_swap_b32_e32 v66, v68
	v_permlane32_swap_b32_e32 v67, v69
	v_permlane32_swap_b32_e32 v156, v158
	v_cvt_pk_bf16_f32 v70, v198, v199
	v_cvt_pk_bf16_f32 v71, v200, v201
	v_cvt_pk_bf16_f32 v72, v202, v203
	v_cvt_pk_bf16_f32 v73, v204, v205
	v_cvt_pk_bf16_f32 v74, v206, v207
	v_cvt_pk_bf16_f32 v75, v208, v209
	v_cvt_pk_bf16_f32 v76, v210, v211
	v_cvt_pk_bf16_f32 v77, v212, v213
	v_cvt_pk_bf16_f32 v78, v157, v159
	v_cvt_pk_bf16_f32 v79, v214, v215
	v_cvt_pk_bf16_f32 v80, v216, v217
	v_cvt_pk_bf16_f32 v81, v218, v81
	v_permlane32_swap_b32_e32 v70, v72
	v_permlane32_swap_b32_e32 v71, v73
	v_permlane32_swap_b32_e32 v74, v76
	v_permlane32_swap_b32_e32 v75, v77
	v_permlane32_swap_b32_e32 v78, v80
	v_permlane32_swap_b32_e32 v79, v81
	v_mfma_f32_32x32x16_bf16 v[98:113], v[188:191], v[126:129], v[98:113]
	v_mfma_f32_32x32x16_bf16 v[82:97], v[192:195], v[126:129], v[82:97]
	ds_read_b64_tr_b16 v[176:177], v169 offset:0
	ds_read_b64_tr_b16 v[178:179], v169 offset:0x800
	ds_read_b64_tr_b16 v[180:181], v169 offset:0x1000
	ds_read_b64_tr_b16 v[182:183], v169 offset:0x1800
	ds_read_b64_tr_b16 v[184:185], v169 offset:0x2000
	ds_read_b64_tr_b16 v[186:187], v169 offset:0x2800
	ds_read_b64_tr_b16 v[188:189], v169 offset:0x3000
	ds_read_b64_tr_b16 v[190:191], v169 offset:0x3800
	ds_read_b64_tr_b16 v[192:193], v169 offset:0x200
	ds_read_b64_tr_b16 v[194:195], v169 offset:0xa00
	ds_read_b64_tr_b16 v[196:197], v169 offset:0x1200
	ds_read_b64_tr_b16 v[198:199], v169 offset:0x1a00
	ds_read_b64_tr_b16 v[200:201], v169 offset:0x2200
	ds_read_b64_tr_b16 v[202:203], v169 offset:0x2a00
	ds_read_b64_tr_b16 v[204:205], v169 offset:0x3200
	ds_read_b64_tr_b16 v[206:207], v169 offset:0x3a00
	s_waitcnt lgkmcnt(8)
	s_nop 0
	v_mfma_f32_32x32x16_bf16 v[2:17], v[66:69], v[176:179], v[2:17]
	s_nop 8
	v_exp_f32_e32 v139, v98
	v_exp_f32_e32 v141, v99
	v_exp_f32_e32 v143, v100
	v_exp_f32_e32 v145, v101
	v_mfma_f32_32x32x16_bf16 v[2:17], v[70:73], v[180:183], v[2:17]
	v_mfma_f32_32x32x16_bf16 v[2:17], v[74:77], v[184:187], v[2:17]
	v_mfma_f32_32x32x16_bf16 v[2:17], v[78:81], v[188:191], v[2:17]
	ds_read_b64_tr_b16 v[98:99], v169 offset:0x400
	ds_read_b64_tr_b16 v[100:101], v169 offset:0xc00
	ds_read_b64_tr_b16 v[176:177], v169 offset:0x1400
	ds_read_b64_tr_b16 v[178:179], v169 offset:0x1c00
	ds_read_b64_tr_b16 v[180:181], v169 offset:0x2400
	ds_read_b64_tr_b16 v[182:183], v169 offset:0x2c00
	ds_read_b64_tr_b16 v[184:185], v169 offset:0x3400
	ds_read_b64_tr_b16 v[186:187], v169 offset:0x3c00
	s_waitcnt lgkmcnt(8)
	v_mfma_f32_32x32x16_bf16 v[18:33], v[66:69], v[192:195], v[18:33]
	v_exp_f32_e32 v147, v102
	v_exp_f32_e32 v149, v103
	v_mfma_f32_32x32x16_bf16 v[18:33], v[70:73], v[196:199], v[18:33]
	v_mfma_f32_32x32x16_bf16 v[18:33], v[74:77], v[200:203], v[18:33]
	v_exp_f32_e32 v200, v104
	v_exp_f32_e32 v201, v105
	v_mfma_f32_32x32x16_bf16 v[18:33], v[78:81], v[204:207], v[18:33]
	ds_read_b64_tr_b16 v[102:103], v169 offset:0x600
	ds_read_b64_tr_b16 v[104:105], v169 offset:0xe00
	ds_read_b64_tr_b16 v[188:189], v169 offset:0x1600
	ds_read_b64_tr_b16 v[190:191], v169 offset:0x1e00
	ds_read_b64_tr_b16 v[192:193], v169 offset:0x2600
	ds_read_b64_tr_b16 v[194:195], v169 offset:0x2e00
	ds_read_b64_tr_b16 v[196:197], v169 offset:0x3600
	ds_read_b64_tr_b16 v[198:199], v169 offset:0x3e00
	s_waitcnt lgkmcnt(8)
	v_mfma_f32_32x32x16_bf16 v[34:49], v[66:69], v[98:101], v[34:49]
	v_exp_f32_e32 v202, v106
	v_exp_f32_e32 v203, v107
	v_exp_f32_e32 v204, v108
	v_exp_f32_e32 v205, v109
	v_mfma_f32_32x32x16_bf16 v[34:49], v[70:73], v[176:179], v[34:49]
	v_mfma_f32_32x32x16_bf16 v[34:49], v[74:77], v[180:183], v[34:49]
	v_mfma_f32_32x32x16_bf16 v[34:49], v[78:81], v[184:187], v[34:49]
	s_waitcnt lgkmcnt(0)
	v_mfma_f32_32x32x16_bf16 v[50:65], v[66:69], v[102:105], v[50:65]
	v_exp_f32_e32 v206, v110
	v_exp_f32_e32 v207, v111
	v_exp_f32_e32 v208, v112
	v_exp_f32_e32 v209, v113
	v_mfma_f32_32x32x16_bf16 v[50:65], v[70:73], v[188:191], v[50:65]
	v_mfma_f32_32x32x16_bf16 v[50:65], v[74:77], v[192:195], v[50:65]
	v_mfma_f32_32x32x16_bf16 v[50:65], v[78:81], v[196:199], v[50:65]
	s_add_u32 s0, s61, 0x18242000
	s_mov_b32 m0, s35
	s_addc_u32 s1, s62, 0
	s_waitcnt vmcnt(0)
	s_waitcnt vmcnt(0)
	s_barrier
	global_load_lds_dwordx4 v[160:161], off
	v_lshl_add_u64 v[66:67], s[0:1], 0, v[152:153]
	s_mov_b32 m0, s56
	s_nop 0
	global_load_lds_dwordx4 v[66:67], off
	v_lshl_add_u64 v[66:67], s[0:1], 0, v[154:155]
	s_mov_b32 m0, s57
	s_nop 0
	global_load_lds_dwordx4 v[66:67], off
	ds_read_b128 v[66:69], v172 offset:40960
	ds_read_b128 v[70:73], v172 offset:45056
	ds_read_b128 v[152:155], v173 offset:40960
	ds_read_b128 v[176:179], v173 offset:45056
	ds_read_b128 v[180:183], v174 offset:40960
	ds_read_b128 v[184:187], v174 offset:45056
	ds_read_b128 v[188:191], v175 offset:40960
	ds_read_b128 v[192:195], v175 offset:45056
	s_waitcnt lgkmcnt(0)
	v_mfma_f32_32x32x16_bf16 v[98:113], v[66:69], v[114:117], 0
	v_exp_f32_e32 v160, v82
	v_exp_f32_e32 v161, v83
	v_exp_f32_e32 v196, v84
	v_exp_f32_e32 v197, v85
	v_exp_f32_e32 v198, v86
	v_exp_f32_e32 v199, v87
	v_exp_f32_e32 v210, v88
	v_mfma_f32_32x32x16_bf16 v[66:81], v[70:73], v[114:117], 0
	v_exp_f32_e32 v211, v89
	v_mfma_f32_32x32x16_bf16 v[66:81], v[176:179], v[118:121], v[66:81]
	v_exp_f32_e32 v212, v94
	v_exp_f32_e32 v213, v95
	v_exp_f32_e32 v214, v96
	v_exp_f32_e32 v97, v97
	v_mfma_f32_32x32x16_bf16 v[98:113], v[152:155], v[118:121], v[98:113]
	v_exp_f32_e32 v152, v90
	v_exp_f32_e32 v153, v91
	v_exp_f32_e32 v154, v92
	v_exp_f32_e32 v155, v93
	v_add_f32_e32 v82, v139, v141
	v_add_f32_e32 v83, v160, v161
	v_mfma_f32_32x32x16_bf16 v[66:81], v[184:187], v[122:125], v[66:81]
	v_add_f32_e32 v82, v82, v143
	v_add_f32_e32 v83, v83, v196
	v_cvt_pk_bf16_f32 v84, v147, v149
	v_add_f32_e32 v82, v82, v145
	v_add_f32_e32 v83, v83, v197
	v_cvt_pk_bf16_f32 v85, v200, v201
	v_add_f32_e32 v82, v82, v147
	v_add_f32_e32 v83, v83, v198
	v_mfma_f32_32x32x16_bf16 v[98:113], v[180:183], v[122:125], v[98:113]
	v_add_f32_e32 v82, v82, v149
	v_add_f32_e32 v83, v83, v199
	s_nop 0
	v_add_f32_e32 v82, v82, v200
	v_add_f32_e32 v83, v83, v210
	s_nop 0
	v_add_f32_e32 v82, v82, v201
	v_add_f32_e32 v83, v83, v211
	s_nop 0
	v_add_f32_e32 v82, v82, v202
	v_add_f32_e32 v83, v83, v152
	s_nop 0
	v_add_f32_e32 v82, v82, v203
	v_add_f32_e32 v83, v83, v153
	s_nop 0
	v_add_f32_e32 v82, v82, v204
	v_add_f32_e32 v83, v83, v154
	s_nop 0
	v_add_f32_e32 v82, v82, v205
	v_add_f32_e32 v83, v83, v155
	s_nop 0
	v_add_f32_e32 v82, v82, v206
	v_add_f32_e32 v83, v83, v212
	s_nop 0
	v_add_f32_e32 v82, v82, v207
	v_add_f32_e32 v83, v83, v213
	s_nop 0
	v_add_f32_e32 v82, v82, v208
	v_add_f32_e32 v83, v83, v214
	s_nop 0
	v_add_f32_e32 v82, v82, v209
	v_add_f32_e32 v83, v83, v97
	s_nop 0
	v_add_f32_e32 v157, v82, v83
	v_mov_b32_e32 v159, v157
	s_nop 1
	v_permlane32_swap_b32_e32 v157, v159
	v_add_f32_e64 v82, v156, v158
	v_add_f32_e64 v83, v157, v159
	v_add_f32_e32 v82, v135, v82
	v_add_f32_e32 v135, v82, v83
	v_cvt_pk_bf16_f32 v82, v139, v141
	v_cvt_pk_bf16_f32 v83, v143, v145
	s_nop 0
	v_permlane32_swap_b32_e32 v82, v84
	v_permlane32_swap_b32_e32 v83, v85
	v_mfma_f32_32x32x16_bf16 v[66:81], v[192:195], v[126:129], v[66:81]
	v_cvt_pk_bf16_f32 v86, v202, v203
	v_cvt_pk_bf16_f32 v87, v204, v205
	v_cvt_pk_bf16_f32 v88, v206, v207
	v_cvt_pk_bf16_f32 v89, v208, v209
	v_cvt_pk_bf16_f32 v90, v160, v161
	v_cvt_pk_bf16_f32 v91, v196, v197
	v_cvt_pk_bf16_f32 v92, v198, v199
	v_cvt_pk_bf16_f32 v93, v210, v211
	v_cvt_pk_bf16_f32 v94, v152, v153
	v_cvt_pk_bf16_f32 v95, v154, v155
	v_cvt_pk_bf16_f32 v96, v212, v213
	v_cvt_pk_bf16_f32 v97, v214, v97
	v_mfma_f32_32x32x16_bf16 v[98:113], v[188:191], v[126:129], v[98:113]
	v_permlane32_swap_b32_e32 v86, v88
	v_permlane32_swap_b32_e32 v87, v89
	v_permlane32_swap_b32_e32 v90, v92
	v_permlane32_swap_b32_e32 v91, v93
	v_permlane32_swap_b32_e32 v94, v96
	v_permlane32_swap_b32_e32 v95, v97
	ds_read_b64_tr_b16 v[152:153], v168 offset:0
	ds_read_b64_tr_b16 v[154:155], v168 offset:0x800
	ds_read_b64_tr_b16 v[156:157], v168 offset:0x1000
	ds_read_b64_tr_b16 v[158:159], v168 offset:0x1800
	ds_read_b64_tr_b16 v[176:177], v168 offset:0x2000
	ds_read_b64_tr_b16 v[178:179], v168 offset:0x2800
	ds_read_b64_tr_b16 v[180:181], v168 offset:0x3000
	ds_read_b64_tr_b16 v[182:183], v168 offset:0x3800
	ds_read_b64_tr_b16 v[184:185], v168 offset:0x200
	ds_read_b64_tr_b16 v[186:187], v168 offset:0xa00
	ds_read_b64_tr_b16 v[188:189], v168 offset:0x1200
	ds_read_b64_tr_b16 v[190:191], v168 offset:0x1a00
	ds_read_b64_tr_b16 v[192:193], v168 offset:0x2200
	ds_read_b64_tr_b16 v[194:195], v168 offset:0x2a00
	ds_read_b64_tr_b16 v[196:197], v168 offset:0x3200
	ds_read_b64_tr_b16 v[198:199], v168 offset:0x3a00
	s_waitcnt lgkmcnt(8)
	s_nop 0
	v_mfma_f32_32x32x16_bf16 v[2:17], v[82:85], v[152:155], v[2:17]
	s_nop 3
	v_exp_f32_e32 v139, v98
	v_exp_f32_e32 v141, v99
	v_exp_f32_e32 v143, v100
	v_exp_f32_e32 v145, v101
	v_mfma_f32_32x32x16_bf16 v[2:17], v[86:89], v[156:159], v[2:17]
	v_mfma_f32_32x32x16_bf16 v[2:17], v[90:93], v[176:179], v[2:17]
	v_mfma_f32_32x32x16_bf16 v[2:17], v[94:97], v[180:183], v[2:17]
	ds_read_b64_tr_b16 v[98:99], v168 offset:0x400
	ds_read_b64_tr_b16 v[100:101], v168 offset:0xc00
	ds_read_b64_tr_b16 v[152:153], v168 offset:0x1400
	ds_read_b64_tr_b16 v[154:155], v168 offset:0x1c00
	ds_read_b64_tr_b16 v[156:157], v168 offset:0x2400
	ds_read_b64_tr_b16 v[158:159], v168 offset:0x2c00
	ds_read_b64_tr_b16 v[200:201], v168 offset:0x3400
	ds_read_b64_tr_b16 v[202:203], v168 offset:0x3c00
	s_waitcnt lgkmcnt(8)
	v_mfma_f32_32x32x16_bf16 v[18:33], v[82:85], v[184:187], v[18:33]
	v_exp_f32_e32 v147, v102
	v_exp_f32_e32 v149, v103
	v_exp_f32_e32 v176, v104
	v_exp_f32_e32 v177, v105
	v_mfma_f32_32x32x16_bf16 v[18:33], v[86:89], v[188:191], v[18:33]
	v_mfma_f32_32x32x16_bf16 v[18:33], v[90:93], v[192:195], v[18:33]
	v_mfma_f32_32x32x16_bf16 v[18:33], v[94:97], v[196:199], v[18:33]
	ds_read_b64_tr_b16 v[102:103], v168 offset:0x600
	ds_read_b64_tr_b16 v[104:105], v168 offset:0xe00
	ds_read_b64_tr_b16 v[182:183], v168 offset:0x1600
	ds_read_b64_tr_b16 v[184:185], v168 offset:0x1e00
	ds_read_b64_tr_b16 v[186:187], v168 offset:0x2600
	ds_read_b64_tr_b16 v[188:189], v168 offset:0x2e00
	ds_read_b64_tr_b16 v[190:191], v168 offset:0x3600
	ds_read_b64_tr_b16 v[192:193], v168 offset:0x3e00
	s_waitcnt lgkmcnt(8)
	v_mfma_f32_32x32x16_bf16 v[34:49], v[82:85], v[98:101], v[34:49]
	v_exp_f32_e32 v178, v106
	v_exp_f32_e32 v179, v107
	v_exp_f32_e32 v180, v108
	v_exp_f32_e32 v181, v109
	v_mfma_f32_32x32x16_bf16 v[34:49], v[86:89], v[152:155], v[34:49]
	v_mfma_f32_32x32x16_bf16 v[34:49], v[90:93], v[156:159], v[34:49]
	v_mfma_f32_32x32x16_bf16 v[34:49], v[94:97], v[200:203], v[34:49]
	s_waitcnt lgkmcnt(0)
	v_mfma_f32_32x32x16_bf16 v[50:65], v[82:85], v[102:105], v[50:65]
	v_mfma_f32_32x32x16_bf16 v[50:65], v[86:89], v[182:185], v[50:65]
	v_exp_f32_e32 v182, v110
	v_exp_f32_e32 v183, v111
	v_exp_f32_e32 v184, v112
	v_exp_f32_e32 v185, v113
	v_mfma_f32_32x32x16_bf16 v[50:65], v[90:93], v[186:189], v[50:65]
	v_mfma_f32_32x32x16_bf16 v[50:65], v[94:97], v[190:193], v[50:65]
	v_add_u32_e32 v82, s60, v163
	v_mul_lo_u32 v82, v82, s22
	v_or3_b32 v82, v162, v82, v137
	v_ashrrev_i32_e32 v83, 31, v82
	v_lshlrev_b64 v[152:153], 1, v[82:83]
	v_add_u32_e32 v82, s59, v163
	v_mul_lo_u32 v82, v82, s22
	v_or3_b32 v82, v162, v82, v137
	s_waitcnt vmcnt(0)
	v_ashrrev_i32_e32 v83, 31, v82
	s_add_u32 s0, s90, s58
	v_lshlrev_b64 v[154:155], 1, v[82:83]
	v_lshl_add_u64 v[150:151], s[52:53], 0, v[150:151]
	s_addc_u32 s1, s91, s25
	v_or_b32_e32 v152, s24, v152
	v_or_b32_e32 v154, s24, v154
	s_mov_b32 s52, 4
	s_waitcnt vmcnt(0)
	s_barrier
	v_exp_f32_e32 v220, v66
	v_exp_f32_e32 v221, v67
	v_exp_f32_e32 v222, v68
	v_exp_f32_e32 v223, v69
	v_exp_f32_e32 v224, v70
	v_exp_f32_e32 v225, v71
	v_exp_f32_e32 v226, v72
	v_exp_f32_e32 v227, v73
	v_exp_f32_e32 v228, v74
	v_exp_f32_e32 v229, v75
	v_exp_f32_e32 v230, v76
	v_exp_f32_e32 v231, v77
	v_exp_f32_e32 v232, v78
	v_exp_f32_e32 v233, v79
	v_exp_f32_e32 v234, v80
	v_exp_f32_e32 v235, v81
	s_branch .LBB0_2320
.LBB0_2319:
	s_mov_b32 m0, s56
	v_lshl_add_u64 v[68:69], v[156:157], 0, s[44:45]
	global_load_lds_dwordx4 v[68:69], off
	v_lshl_add_u64 v[68:69], v[158:159], 0, s[44:45]
	s_mov_b32 m0, s57
	global_load_lds_dwordx4 v[68:69], off
	ds_read_b128 v[68:71], v172 offset:40960
	ds_read_b128 v[72:75], v172 offset:45056
	ds_read_b128 v[156:159], v173 offset:40960
	ds_read_b128 v[176:179], v173 offset:45056
	ds_read_b128 v[180:183], v174 offset:40960
	ds_read_b128 v[184:187], v174 offset:45056
	ds_read_b128 v[188:191], v175 offset:40960
	ds_read_b128 v[192:195], v175 offset:45056
	v_add_f32_e32 v66, v66, v67
	v_add_f32_e32 v135, v135, v66
	s_add_i32 s52, s52, 2
	s_waitcnt lgkmcnt(0)
	v_mfma_f32_32x32x16_bf16 v[98:113], v[68:71], v[114:117], 0
	v_mfma_f32_32x32x16_bf16 v[66:81], v[72:75], v[114:117], 0
	v_mfma_f32_32x32x16_bf16 v[66:81], v[176:179], v[118:121], v[66:81]
	v_mfma_f32_32x32x16_bf16 v[98:113], v[156:159], v[118:121], v[98:113]
	v_add_f32_e32 v82, v236, v237
	v_add_f32_e32 v83, v220, v221
	v_mfma_f32_32x32x16_bf16 v[66:81], v[184:187], v[122:125], v[66:81]
	v_add_f32_e32 v82, v82, v238
	v_add_f32_e32 v83, v83, v222
	v_cvt_pk_bf16_f32 v84, v240, v241
	v_add_f32_e32 v82, v82, v239
	v_add_f32_e32 v83, v83, v223
	v_cvt_pk_bf16_f32 v85, v244, v245
	v_add_f32_e32 v82, v82, v240
	v_add_f32_e32 v83, v83, v224
	v_mfma_f32_32x32x16_bf16 v[98:113], v[180:183], v[122:125], v[98:113]
	v_add_f32_e32 v82, v82, v241
	v_add_f32_e32 v83, v83, v225
	v_add_f32_e32 v82, v82, v244
	v_add_f32_e32 v83, v83, v226
	v_add_f32_e32 v82, v82, v245
	v_add_f32_e32 v83, v83, v227
	v_add_f32_e32 v82, v82, v246
	v_add_f32_e32 v83, v83, v228
	v_add_f32_e32 v82, v82, v247
	v_add_f32_e32 v83, v83, v229
	v_add_f32_e32 v82, v82, v248
	v_add_f32_e32 v83, v83, v230
	v_add_f32_e32 v82, v82, v249
	v_add_f32_e32 v83, v83, v231
	v_add_f32_e32 v82, v82, v250
	v_add_f32_e32 v83, v83, v232
	v_add_f32_e32 v82, v82, v251
	v_add_f32_e32 v83, v83, v233
	v_add_f32_e32 v82, v82, v252
	v_add_f32_e32 v83, v83, v234
	v_add_f32_e32 v82, v82, v253
	v_add_f32_e32 v83, v83, v235
	v_add_f32_e32 v82, v82, v83
	v_mov_b32_e32 v83, v82
	s_nop 1
	v_permlane32_swap_b32_e32 v82, v83
	v_add_f32_e32 v82, v82, v83
	v_add_f32_e32 v135, v135, v82
	v_cvt_pk_bf16_f32 v82, v236, v237
	v_cvt_pk_bf16_f32 v83, v238, v239
	s_nop 0
	v_permlane32_swap_b32_e32 v82, v84
	v_permlane32_swap_b32_e32 v83, v85
	v_mfma_f32_32x32x16_bf16 v[66:81], v[192:195], v[126:129], v[66:81]
	v_cvt_pk_bf16_f32 v86, v246, v247
	v_cvt_pk_bf16_f32 v87, v248, v249
	v_cvt_pk_bf16_f32 v88, v250, v251
	v_cvt_pk_bf16_f32 v89, v252, v253
	v_cvt_pk_bf16_f32 v90, v220, v221
	v_cvt_pk_bf16_f32 v91, v222, v223
	v_cvt_pk_bf16_f32 v92, v224, v225
	v_cvt_pk_bf16_f32 v93, v226, v227
	v_cvt_pk_bf16_f32 v94, v228, v229
	v_cvt_pk_bf16_f32 v95, v230, v231
	v_cvt_pk_bf16_f32 v96, v232, v233
	v_cvt_pk_bf16_f32 v97, v234, v235
	v_mfma_f32_32x32x16_bf16 v[98:113], v[188:191], v[126:129], v[98:113]
	v_permlane32_swap_b32_e32 v86, v88
	v_permlane32_swap_b32_e32 v87, v89
	v_permlane32_swap_b32_e32 v90, v92
	v_permlane32_swap_b32_e32 v91, v93
	v_permlane32_swap_b32_e32 v94, v96
	v_permlane32_swap_b32_e32 v95, v97
	ds_read_b64_tr_b16 v[156:157], v168 offset:0
	ds_read_b64_tr_b16 v[158:159], v168 offset:0x800
	ds_read_b64_tr_b16 v[176:177], v168 offset:0x1000
	ds_read_b64_tr_b16 v[178:179], v168 offset:0x1800
	ds_read_b64_tr_b16 v[180:181], v168 offset:0x2000
	ds_read_b64_tr_b16 v[182:183], v168 offset:0x2800
	ds_read_b64_tr_b16 v[184:185], v168 offset:0x3000
	ds_read_b64_tr_b16 v[186:187], v168 offset:0x3800
	ds_read_b64_tr_b16 v[188:189], v168 offset:0x200
	ds_read_b64_tr_b16 v[190:191], v168 offset:0xa00
	ds_read_b64_tr_b16 v[192:193], v168 offset:0x1200
	ds_read_b64_tr_b16 v[194:195], v168 offset:0x1a00
	ds_read_b64_tr_b16 v[196:197], v168 offset:0x2200
	ds_read_b64_tr_b16 v[198:199], v168 offset:0x2a00
	ds_read_b64_tr_b16 v[200:201], v168 offset:0x3200
	ds_read_b64_tr_b16 v[202:203], v168 offset:0x3a00
	s_waitcnt lgkmcnt(8)
	s_nop 0
	v_mfma_f32_32x32x16_bf16 v[2:17], v[82:85], v[156:159], v[2:17]
	v_exp_f32_e32 v220, v66
	s_nop 3
	v_exp_f32_e32 v139, v98
	v_exp_f32_e32 v141, v99
	v_exp_f32_e32 v143, v100
	v_exp_f32_e32 v145, v101
	v_mfma_f32_32x32x16_bf16 v[2:17], v[86:89], v[176:179], v[2:17]
	v_exp_f32_e32 v221, v67
	v_mfma_f32_32x32x16_bf16 v[2:17], v[90:93], v[180:183], v[2:17]
	v_exp_f32_e32 v222, v68
	v_mfma_f32_32x32x16_bf16 v[2:17], v[94:97], v[184:187], v[2:17]
	v_exp_f32_e32 v223, v69
	ds_read_b64_tr_b16 v[98:99], v168 offset:0x400
	ds_read_b64_tr_b16 v[100:101], v168 offset:0xc00
	ds_read_b64_tr_b16 v[156:157], v168 offset:0x1400
	ds_read_b64_tr_b16 v[158:159], v168 offset:0x1c00
	ds_read_b64_tr_b16 v[178:179], v168 offset:0x2400
	ds_read_b64_tr_b16 v[180:181], v168 offset:0x2c00
	ds_read_b64_tr_b16 v[182:183], v168 offset:0x3400
	ds_read_b64_tr_b16 v[184:185], v168 offset:0x3c00
	s_waitcnt lgkmcnt(8)
	v_mfma_f32_32x32x16_bf16 v[18:33], v[82:85], v[188:191], v[18:33]
	v_exp_f32_e32 v224, v70
	v_exp_f32_e32 v147, v102
	v_exp_f32_e32 v149, v103
	v_exp_f32_e32 v176, v104
	v_exp_f32_e32 v177, v105
	v_mfma_f32_32x32x16_bf16 v[18:33], v[86:89], v[192:195], v[18:33]
	v_exp_f32_e32 v225, v71
	v_mfma_f32_32x32x16_bf16 v[18:33], v[90:93], v[196:199], v[18:33]
	v_exp_f32_e32 v226, v72
	v_mfma_f32_32x32x16_bf16 v[18:33], v[94:97], v[200:203], v[18:33]
	v_exp_f32_e32 v227, v73
	ds_read_b64_tr_b16 v[102:103], v168 offset:0x600
	ds_read_b64_tr_b16 v[104:105], v168 offset:0xe00
	ds_read_b64_tr_b16 v[186:187], v168 offset:0x1600
	ds_read_b64_tr_b16 v[188:189], v168 offset:0x1e00
	ds_read_b64_tr_b16 v[190:191], v168 offset:0x2600
	ds_read_b64_tr_b16 v[192:193], v168 offset:0x2e00
	ds_read_b64_tr_b16 v[194:195], v168 offset:0x3600
	ds_read_b64_tr_b16 v[196:197], v168 offset:0x3e00
	s_waitcnt lgkmcnt(8)
	v_mfma_f32_32x32x16_bf16 v[34:49], v[82:85], v[98:101], v[34:49]
	v_exp_f32_e32 v228, v74
	v_mfma_f32_32x32x16_bf16 v[34:49], v[86:89], v[156:159], v[34:49]
	v_exp_f32_e32 v229, v75
	v_mfma_f32_32x32x16_bf16 v[34:49], v[90:93], v[178:181], v[34:49]
	v_exp_f32_e32 v230, v76
	v_exp_f32_e32 v178, v106
	v_exp_f32_e32 v179, v107
	v_exp_f32_e32 v180, v108
	v_exp_f32_e32 v181, v109
	v_mfma_f32_32x32x16_bf16 v[34:49], v[94:97], v[182:185], v[34:49]
	v_exp_f32_e32 v231, v77
	s_waitcnt lgkmcnt(0)
	v_mfma_f32_32x32x16_bf16 v[50:65], v[82:85], v[102:105], v[50:65]
	v_exp_f32_e32 v232, v78
	v_exp_f32_e32 v182, v110
	v_exp_f32_e32 v183, v111
	v_exp_f32_e32 v184, v112
	v_exp_f32_e32 v185, v113
	v_mfma_f32_32x32x16_bf16 v[50:65], v[86:89], v[186:189], v[50:65]
	v_exp_f32_e32 v233, v79
	v_mfma_f32_32x32x16_bf16 v[50:65], v[90:93], v[190:193], v[50:65]
	v_exp_f32_e32 v234, v80
	v_mfma_f32_32x32x16_bf16 v[50:65], v[94:97], v[194:197], v[50:65]
	v_exp_f32_e32 v235, v81
	s_waitcnt vmcnt(0)
	s_add_u32 s0, s0, 0x180000
	s_addc_u32 s1, s1, 0
	s_and_b64 vcc, exec, s[24:25]
	s_waitcnt vmcnt(0)
	s_barrier
	s_cbranch_vccnz .LBB0_2322
.LBB0_2320:
	v_lshl_add_u64 v[160:161], s[0:1], 0, v[150:151]
	s_mov_b32 m0, s55
	v_lshl_add_u64 v[82:83], v[160:161], 0, s[18:19]
	v_lshl_add_u64 v[156:157], s[0:1], 0, v[152:153]
	global_load_lds_dwordx4 v[82:83], off
	v_lshl_add_u64 v[82:83], v[156:157], 0, s[36:37]
	s_mov_b32 m0, s34
	v_lshl_add_u64 v[158:159], s[0:1], 0, v[154:155]
	global_load_lds_dwordx4 v[82:83], off
	v_lshl_add_u64 v[82:83], v[158:159], 0, s[36:37]
	s_mov_b32 m0, s54
	s_nop 0
	global_load_lds_dwordx4 v[82:83], off
	ds_read_b128 v[82:85], v172 offset:32768
	ds_read_b128 v[86:89], v172 offset:36864
	ds_read_b128 v[186:189], v173 offset:32768
	ds_read_b128 v[190:193], v173 offset:36864
	ds_read_b128 v[194:197], v174 offset:32768
	ds_read_b128 v[198:201], v174 offset:36864
	ds_read_b128 v[202:205], v175 offset:32768
	ds_read_b128 v[206:209], v175 offset:36864
	s_waitcnt lgkmcnt(0)
	v_mfma_f32_32x32x16_bf16 v[98:113], v[82:85], v[114:117], 0
	v_mfma_f32_32x32x16_bf16 v[82:97], v[86:89], v[114:117], 0
	v_mfma_f32_32x32x16_bf16 v[98:113], v[186:189], v[118:121], v[98:113]
	v_mfma_f32_32x32x16_bf16 v[82:97], v[190:193], v[118:121], v[82:97]
	v_add_f32_e32 v66, v139, v141
	v_add_f32_e32 v67, v220, v221
	v_mfma_f32_32x32x16_bf16 v[98:113], v[194:197], v[122:125], v[98:113]
	v_add_f32_e32 v66, v66, v143
	v_add_f32_e32 v67, v67, v222
	v_cvt_pk_bf16_f32 v68, v139, v141
	v_add_f32_e32 v66, v66, v145
	v_add_f32_e32 v67, v67, v223
	v_cvt_pk_bf16_f32 v69, v143, v145
	v_add_f32_e32 v66, v66, v147
	v_add_f32_e32 v67, v67, v224
	v_mfma_f32_32x32x16_bf16 v[82:97], v[198:201], v[122:125], v[82:97]
	v_add_f32_e32 v66, v66, v149
	v_add_f32_e32 v67, v67, v225
	v_cvt_pk_bf16_f32 v70, v147, v149
	v_add_f32_e32 v66, v66, v176
	v_add_f32_e32 v67, v67, v226
	v_cvt_pk_bf16_f32 v71, v176, v177
	v_add_f32_e32 v66, v66, v177
	v_add_f32_e32 v67, v67, v227
	s_nop 0
	v_permlane32_swap_b32_e32 v68, v70
	v_add_f32_e32 v66, v66, v178
	v_add_f32_e32 v67, v67, v228
	v_permlane32_swap_b32_e32 v69, v71
	v_add_f32_e32 v66, v66, v179
	v_add_f32_e32 v67, v67, v229
	v_add_f32_e32 v66, v66, v180
	v_add_f32_e32 v67, v67, v230
	v_add_f32_e32 v66, v66, v181
	v_add_f32_e32 v67, v67, v231
	v_add_f32_e32 v66, v66, v182
	v_add_f32_e32 v67, v67, v232
	v_add_f32_e32 v66, v66, v183
	v_add_f32_e32 v67, v67, v233
	v_add_f32_e32 v66, v66, v184
	v_add_f32_e32 v67, v67, v234
	v_add_f32_e32 v66, v66, v185
	v_add_f32_e32 v67, v67, v235
	v_add_f32_e32 v66, v66, v67
	v_mov_b32_e32 v67, v66
	s_nop 1
	v_permlane32_swap_b32_e32 v66, v67
	v_mfma_f32_32x32x16_bf16 v[98:113], v[202:205], v[126:129], v[98:113]
	v_cvt_pk_bf16_f32 v72, v178, v179
	v_cvt_pk_bf16_f32 v73, v180, v181
	v_cvt_pk_bf16_f32 v74, v182, v183
	v_cvt_pk_bf16_f32 v75, v184, v185
	v_cvt_pk_bf16_f32 v76, v220, v221
	v_cvt_pk_bf16_f32 v77, v222, v223
	v_cvt_pk_bf16_f32 v78, v224, v225
	v_mfma_f32_32x32x16_bf16 v[82:97], v[206:209], v[126:129], v[82:97]
	v_cvt_pk_bf16_f32 v79, v226, v227
	v_cvt_pk_bf16_f32 v176, v228, v229
	v_cvt_pk_bf16_f32 v177, v230, v231
	v_cvt_pk_bf16_f32 v178, v232, v233
	v_cvt_pk_bf16_f32 v179, v234, v235
	v_permlane32_swap_b32_e32 v72, v74
	v_permlane32_swap_b32_e32 v73, v75
	v_permlane32_swap_b32_e32 v76, v78
	v_permlane32_swap_b32_e32 v77, v79
	v_permlane32_swap_b32_e32 v176, v178
	v_permlane32_swap_b32_e32 v177, v179
	ds_read_b64_tr_b16 v[180:181], v169 offset:0
	ds_read_b64_tr_b16 v[182:183], v169 offset:0x800
	ds_read_b64_tr_b16 v[184:185], v169 offset:0x1000
	ds_read_b64_tr_b16 v[186:187], v169 offset:0x1800
	ds_read_b64_tr_b16 v[188:189], v169 offset:0x2000
	ds_read_b64_tr_b16 v[190:191], v169 offset:0x2800
	ds_read_b64_tr_b16 v[192:193], v169 offset:0x3000
	ds_read_b64_tr_b16 v[194:195], v169 offset:0x3800
	ds_read_b64_tr_b16 v[196:197], v169 offset:0x200
	ds_read_b64_tr_b16 v[198:199], v169 offset:0xa00
	ds_read_b64_tr_b16 v[200:201], v169 offset:0x1200
	ds_read_b64_tr_b16 v[202:203], v169 offset:0x1a00
	ds_read_b64_tr_b16 v[204:205], v169 offset:0x2200
	ds_read_b64_tr_b16 v[206:207], v169 offset:0x2a00
	ds_read_b64_tr_b16 v[208:209], v169 offset:0x3200
	ds_read_b64_tr_b16 v[210:211], v169 offset:0x3a00
	s_waitcnt lgkmcnt(8)
	s_nop 0
	v_mfma_f32_32x32x16_bf16 v[2:17], v[68:71], v[180:183], v[2:17]
	v_exp_f32_e32 v236, v98
	v_exp_f32_e32 v237, v99
	v_mfma_f32_32x32x16_bf16 v[2:17], v[72:75], v[184:187], v[2:17]
	v_exp_f32_e32 v238, v100
	v_exp_f32_e32 v239, v101
	v_mfma_f32_32x32x16_bf16 v[2:17], v[76:79], v[188:191], v[2:17]
	v_exp_f32_e32 v240, v102
	v_exp_f32_e32 v241, v103
	v_mfma_f32_32x32x16_bf16 v[2:17], v[176:179], v[192:195], v[2:17]
	v_exp_f32_e32 v244, v104
	v_exp_f32_e32 v245, v105
	ds_read_b64_tr_b16 v[180:181], v169 offset:0x400
	ds_read_b64_tr_b16 v[182:183], v169 offset:0xc00
	ds_read_b64_tr_b16 v[184:185], v169 offset:0x1400
	ds_read_b64_tr_b16 v[186:187], v169 offset:0x1c00
	ds_read_b64_tr_b16 v[188:189], v169 offset:0x2400
	ds_read_b64_tr_b16 v[190:191], v169 offset:0x2c00
	ds_read_b64_tr_b16 v[192:193], v169 offset:0x3400
	ds_read_b64_tr_b16 v[194:195], v169 offset:0x3c00
	s_waitcnt lgkmcnt(8)
	v_mfma_f32_32x32x16_bf16 v[18:33], v[68:71], v[196:199], v[18:33]
	v_exp_f32_e32 v246, v106
	v_exp_f32_e32 v247, v107
	v_mfma_f32_32x32x16_bf16 v[18:33], v[72:75], v[200:203], v[18:33]
	v_exp_f32_e32 v248, v108
	v_exp_f32_e32 v249, v109
	v_mfma_f32_32x32x16_bf16 v[18:33], v[76:79], v[204:207], v[18:33]
	v_exp_f32_e32 v250, v110
	v_exp_f32_e32 v251, v111
	v_mfma_f32_32x32x16_bf16 v[18:33], v[176:179], v[208:211], v[18:33]
	v_exp_f32_e32 v252, v112
	v_exp_f32_e32 v253, v113
	ds_read_b64_tr_b16 v[196:197], v169 offset:0x600
	ds_read_b64_tr_b16 v[198:199], v169 offset:0xe00
	ds_read_b64_tr_b16 v[200:201], v169 offset:0x1600
	ds_read_b64_tr_b16 v[202:203], v169 offset:0x1e00
	ds_read_b64_tr_b16 v[204:205], v169 offset:0x2600
	ds_read_b64_tr_b16 v[206:207], v169 offset:0x2e00
	ds_read_b64_tr_b16 v[208:209], v169 offset:0x3600
	ds_read_b64_tr_b16 v[210:211], v169 offset:0x3e00
	s_waitcnt lgkmcnt(8)
	v_mfma_f32_32x32x16_bf16 v[34:49], v[68:71], v[180:183], v[34:49]
	v_exp_f32_e32 v220, v82
	v_exp_f32_e32 v221, v83
	v_mfma_f32_32x32x16_bf16 v[34:49], v[72:75], v[184:187], v[34:49]
	v_exp_f32_e32 v222, v84
	v_exp_f32_e32 v223, v85
	v_mfma_f32_32x32x16_bf16 v[34:49], v[76:79], v[188:191], v[34:49]
	v_exp_f32_e32 v224, v86
	v_exp_f32_e32 v225, v87
	v_mfma_f32_32x32x16_bf16 v[34:49], v[176:179], v[192:195], v[34:49]
	v_exp_f32_e32 v226, v88
	v_exp_f32_e32 v227, v89
	s_waitcnt lgkmcnt(0)
	v_mfma_f32_32x32x16_bf16 v[50:65], v[68:71], v[196:199], v[50:65]
	v_exp_f32_e32 v228, v90
	v_exp_f32_e32 v229, v91
	v_mfma_f32_32x32x16_bf16 v[50:65], v[72:75], v[200:203], v[50:65]
	v_exp_f32_e32 v230, v92
	v_exp_f32_e32 v231, v93
	v_mfma_f32_32x32x16_bf16 v[50:65], v[76:79], v[204:207], v[50:65]
	v_exp_f32_e32 v232, v94
	v_exp_f32_e32 v233, v95
	v_mfma_f32_32x32x16_bf16 v[50:65], v[176:179], v[208:211], v[50:65]
	v_exp_f32_e32 v234, v96
	v_exp_f32_e32 v235, v97
	s_waitcnt vmcnt(0)
	s_cmpk_gt_u32 s52, 0x101
	s_cselect_b64 s[24:25], -1, 0
	s_and_b64 vcc, exec, s[24:25]
	s_waitcnt vmcnt(0)
	s_barrier
	s_cbranch_vccnz .LBB0_2319
	v_lshl_add_u64 v[68:69], v[160:161], 0, s[38:39]
	s_mov_b32 m0, s35
	s_nop 0
	global_load_lds_dwordx4 v[68:69], off
	s_branch .LBB0_2319
